# K-loop MFMA blocks start on 8-byte boundaries (alignment padding in the load segment)
# speedup vs baseline: 1.0091x; 1.0061x over previous
; #define PG8_STAGE(bufoff, gbase, voff) do { _Pragma("unroll") for (int _i = 0; _i < 2; ++_i) \
;         __builtin_amdgcn_global_load_lds((const unsigned*)((const char*)(gbase) + (voff)[_i]), (PG8_LAS unsigned*)(lds + (bufoff) + ldsw + _i * 8192), 16, 0, 0); } while (0)
; #define PG8_LDA(dst, b, h) do { _Pragma("unroll") for (int m = 0; m < 4; ++m) _Pragma("unroll") for (int k = 0; k < 2; ++k) dst[m][k] = *(const PG8_LAS bf16x8*)(lds + PG8_SA(b, h) + aoff + m * 2048 + k * 1024); } while (0)
; #define PG8_LDB(dst, b, h) do { _Pragma("unroll") for (int n = 0; n < 2; ++n) _Pragma("unroll") for (int k = 0; k < 2; ++k) dst[n][k] = *(const PG8_LAS bf16x8*)(lds + PG8_SB(b, h) + boff + n * 2048 + k * 1024); } while (0)
; #define PG8_MMA(ai, bj, At, Bt) do { __builtin_amdgcn_s_setprio(1); _Pragma("unroll") for (int m = 0; m < 4; ++m) _Pragma("unroll") for (int n = 0; n < 2; ++n) _Pragma("unroll") for (int k = 0; k < 2; ++k) \
;         acc[ai][bj][m][n] = __builtin_amdgcn_mfma_f32_16x16x32_bf16(Bt[n][k], At[m][k], acc[ai][bj][m][n], 0, 0, 0); __builtin_amdgcn_s_setprio(0); } while (0)
; #define PG8_WAIT_V(n) asm volatile("s_waitcnt vmcnt(" #n ")" ::: "memory")
; #define PG8_BAR __builtin_amdgcn_s_barrier()
; template <class Epi, class Sched, bool ALIGN_EPI = false, bool SP2 = false>
; __device__ __forceinline__ void gemm_phase(PG8_LAS unsigned char* lds, const Gemm g, const Sched& S, const Epi& E) {
;     ...
;             const bool last = (t == nt - 2);
;             const char* a1 = cA + (size_t)(t + 1) * kstep;
;             const char* a2 = last ? nA : cA + (size_t)(t + 2) * kstep; const char* b2 = last ? nB : cB + (size_t)(t + 2) * kstep;
;             const char* a3 = a2 + kstep; const char* b3 = b2 + kstep;
;             if (last && has_next) S.a_ready(nxt);
;             if (last) E.pre(cur, wid, lane);
;             if constexpr (SP2) {
;             PG8_LDB(B0, 0, 0); PG8_LDB(B1, 0, 1); PG8_SCHED; PG8_LDA(At, 0, 0); PG8_STAGE(PG8_SA(1, 1), a1 + hstep, voffA);
;             PG8_WAIT_V(8); PG8_WAIT_L(0); PG8_BAR; PG8_MMA(0, 0, At, B0); PG8_MMA(0, 1, At, B1); PG8_BAR; PG8_SCHED;
;             PG8_LDA(At, 0, 1); PG8_STAGE(PG8_SB(0, 0), b2, voffB); PG8_STAGE(PG8_SB(0, 1), b2 + hstep, voffB); PG8_STAGE(PG8_SA(0, 0), a2, voffA);
;             PG8_WAIT_V(8); PG8_WAIT_L(0); PG8_BAR; PG8_MMA(1, 0, At, B0); PG8_MMA(1, 1, At, B1); PG8_BAR; PG8_SCHED;
.LBB0_244:
	s_add_u32 s6, s4, 0xfffc0080
	s_addc_u32 s7, s5, -1
	s_and_b64 s[0:1], s[0:1], exec
	s_cselect_b32 s7, s38, s7
	s_cselect_b32 s6, s39, s6
	s_cselect_b32 s1, s49, s57
	s_cselect_b32 s0, s55, s56
	s_add_i32 s59, 0, 0x10000
	v_add_u32_e32 v144, s59, v197
	s_add_i32 s62, 0, 0x14000
	ds_read_b128 v[132:135], v144
	ds_read_b128 v[136:139], v144 offset:1024
	ds_read_b128 v[140:143], v144 offset:2048
	ds_read_b128 v[202:205], v144 offset:3072
	v_add_u32_e32 v144, s62, v197
	ds_read_b128 v[206:209], v144
	ds_read_b128 v[210:213], v144 offset:1024
	ds_read_b128 v[214:217], v144 offset:2048
	ds_read_b128 v[218:221], v144 offset:3072
	v_lshl_add_u64 v[172:173], s[4:5], 0, v[166:167]
	s_add_i32 m0, s25, 0xc000
	ds_read_b128 v[222:225], v199
	ds_read_b128 v[226:229], v199 offset:1024
	ds_read_b128 v[230:233], v199 offset:2048
	ds_read_b128 v[234:237], v199 offset:3072
	ds_read_b128 v[238:241], v199 offset:4096
	ds_read_b128 v[242:245], v199 offset:5120
	ds_read_b128 v[246:249], v199 offset:6144
	ds_read_b128 v[180:183], v199 offset:7168
	global_load_lds_dwordx4 v[172:173], off
	v_lshl_add_u64 v[172:173], s[4:5], 0, v[168:169]
	s_add_i32 m0, s25, 0xe000
	s_nop 0
	global_load_lds_dwordx4 v[172:173], off
	s_waitcnt vmcnt(8)
	s_waitcnt lgkmcnt(0)
	.p2alignl 3, 3212836864
	s_setprio 1
	s_barrier
	v_mfma_f32_16x16x32_bf16 v[124:127], v[132:135], v[222:225], v[124:127]
	v_mfma_f32_16x16x32_bf16 v[120:123], v[140:143], v[222:225], v[120:123]
	v_mfma_f32_16x16x32_bf16 v[108:111], v[132:135], v[230:233], v[108:111]
	v_mfma_f32_16x16x32_bf16 v[104:107], v[140:143], v[230:233], v[104:107]
	v_mfma_f32_16x16x32_bf16 v[92:95], v[132:135], v[238:241], v[92:95]
	v_mfma_f32_16x16x32_bf16 v[88:91], v[140:143], v[238:241], v[88:91]
	v_mfma_f32_16x16x32_bf16 v[76:79], v[132:135], v[246:249], v[76:79]
	v_mfma_f32_16x16x32_bf16 v[72:75], v[140:143], v[246:249], v[72:75]
	v_mfma_f32_16x16x32_bf16 v[124:127], v[136:139], v[226:229], v[124:127]
	v_mfma_f32_16x16x32_bf16 v[120:123], v[202:205], v[226:229], v[120:123]
	v_mfma_f32_16x16x32_bf16 v[108:111], v[136:139], v[234:237], v[108:111]
	v_mfma_f32_16x16x32_bf16 v[104:107], v[202:205], v[234:237], v[104:107]
	v_mfma_f32_16x16x32_bf16 v[92:95], v[136:139], v[242:245], v[92:95]
	v_mfma_f32_16x16x32_bf16 v[88:91], v[202:205], v[242:245], v[88:91]
	v_mfma_f32_16x16x32_bf16 v[76:79], v[136:139], v[180:183], v[76:79]
	v_mfma_f32_16x16x32_bf16 v[72:75], v[202:205], v[180:183], v[72:75]
	s_setprio 0
	s_setprio 1
	v_mfma_f32_16x16x32_bf16 v[116:119], v[206:209], v[222:225], v[116:119]
	v_mfma_f32_16x16x32_bf16 v[112:115], v[214:217], v[222:225], v[112:115]
	v_mfma_f32_16x16x32_bf16 v[100:103], v[206:209], v[230:233], v[100:103]
	v_mfma_f32_16x16x32_bf16 v[96:99], v[214:217], v[230:233], v[96:99]
	v_mfma_f32_16x16x32_bf16 v[84:87], v[206:209], v[238:241], v[84:87]
	v_mfma_f32_16x16x32_bf16 v[80:83], v[214:217], v[238:241], v[80:83]
	v_mfma_f32_16x16x32_bf16 v[68:71], v[206:209], v[246:249], v[68:71]
	v_mfma_f32_16x16x32_bf16 v[64:67], v[214:217], v[246:249], v[64:67]
	v_mfma_f32_16x16x32_bf16 v[116:119], v[210:213], v[226:229], v[116:119]
	v_mfma_f32_16x16x32_bf16 v[112:115], v[218:221], v[226:229], v[112:115]
	v_mfma_f32_16x16x32_bf16 v[100:103], v[210:213], v[234:237], v[100:103]
	v_mfma_f32_16x16x32_bf16 v[96:99], v[218:221], v[234:237], v[96:99]
	v_mfma_f32_16x16x32_bf16 v[84:87], v[210:213], v[242:245], v[84:87]
	v_mfma_f32_16x16x32_bf16 v[80:83], v[218:221], v[242:245], v[80:83]
	v_mfma_f32_16x16x32_bf16 v[68:71], v[210:213], v[180:183], v[68:71]
	v_mfma_f32_16x16x32_bf16 v[64:67], v[218:221], v[180:183], v[64:67]
	s_barrier
	s_setprio 0
	s_add_i32 s59, s59, s24
	v_lshl_add_u64 v[172:173], s[0:1], 0, v[154:155]
	s_mov_b32 m0, s59
	ds_read_b128 v[180:183], v199 offset:16384
	ds_read_b128 v[222:225], v199 offset:17408
	ds_read_b128 v[226:229], v199 offset:18432
	ds_read_b128 v[230:233], v199 offset:19456
	ds_read_b128 v[234:237], v199 offset:20480
	ds_read_b128 v[238:241], v199 offset:21504
	ds_read_b128 v[242:245], v199 offset:22528
	ds_read_b128 v[246:249], v199 offset:23552
	global_load_lds_dwordx4 v[172:173], off
	s_add_i32 m0, s59, 0x2000
	s_add_u32 s60, s0, 0x40000
	v_lshl_add_u64 v[184:185], s[0:1], 0, v[150:151]
	s_addc_u32 s61, s1, 0
	s_add_i32 s59, s62, s24
	global_load_lds_dwordx4 v[184:185], off
	v_lshl_add_u64 v[186:187], s[60:61], 0, v[154:155]
	s_mov_b32 m0, s59
	v_lshl_add_u64 v[188:189], s[6:7], 0, v[152:153]
	global_load_lds_dwordx4 v[186:187], off
	v_lshl_add_u64 v[186:187], s[60:61], 0, v[150:151]
	s_add_i32 m0, s59, 0x2000
	s_nop 0
	global_load_lds_dwordx4 v[186:187], off
	v_lshl_add_u64 v[186:187], s[6:7], 0, v[156:157]
	s_mov_b32 m0, s25
	s_nop 0
	global_load_lds_dwordx4 v[186:187], off
	s_mov_b32 m0, s26
	s_nop 0
	global_load_lds_dwordx4 v[188:189], off
	s_waitcnt vmcnt(8)
	s_waitcnt lgkmcnt(0)
	.p2alignl 3, 3212836864
	s_setprio 1
	s_barrier
; #define PG8_STAGE(bufoff, gbase, voff) do { _Pragma("unroll") for (int _i = 0; _i < 2; ++_i) \
;         __builtin_amdgcn_global_load_lds((const unsigned*)((const char*)(gbase) + (voff)[_i]), (PG8_LAS unsigned*)(lds + (bufoff) + ldsw + _i * 8192), 16, 0, 0); } while (0)
; #define PG8_LDA(dst, b, h) do { _Pragma("unroll") for (int m = 0; m < 4; ++m) _Pragma("unroll") for (int k = 0; k < 2; ++k) dst[m][k] = *(const PG8_LAS bf16x8*)(lds + PG8_SA(b, h) + aoff + m * 2048 + k * 1024); } while (0)
; #define PG8_LDB(dst, b, h) do { _Pragma("unroll") for (int n = 0; n < 2; ++n) _Pragma("unroll") for (int k = 0; k < 2; ++k) dst[n][k] = *(const PG8_LAS bf16x8*)(lds + PG8_SB(b, h) + boff + n * 2048 + k * 1024); } while (0)
; #define PG8_MMA(ai, bj, At, Bt) do { __builtin_amdgcn_s_setprio(1); _Pragma("unroll") for (int m = 0; m < 4; ++m) _Pragma("unroll") for (int n = 0; n < 2; ++n) _Pragma("unroll") for (int k = 0; k < 2; ++k) \
;         acc[ai][bj][m][n] = __builtin_amdgcn_mfma_f32_16x16x32_bf16(Bt[n][k], At[m][k], acc[ai][bj][m][n], 0, 0, 0); __builtin_amdgcn_s_setprio(0); } while (0)
; #define PG8_WAIT_V(n) asm volatile("s_waitcnt vmcnt(" #n ")" ::: "memory")
; #define PG8_WAIT_L(n) asm volatile("s_waitcnt lgkmcnt(" #n ")" ::: "memory")
; #define PG8_BAR __builtin_amdgcn_s_barrier()
; #define PG8_SCHED __builtin_amdgcn_sched_barrier(0)
; template <class Epi, class Sched, bool ALIGN_EPI = false, bool SP2 = false>
; __device__ __forceinline__ void gemm_phase(PG8_LAS unsigned char* lds, const Gemm g, const Sched& S, const Epi& E) {
;     ...
;             PG8_WAIT_V(8); PG8_WAIT_L(0); PG8_BAR; PG8_MMA(1, 0, At, B0); PG8_MMA(1, 1, At, B1); PG8_BAR; PG8_SCHED;
;             PG8_LDB(B0, 1, 0); PG8_LDB(B1, 1, 1); PG8_SCHED; PG8_LDA(At, 1, 0); PG8_STAGE(PG8_SA(0, 1), a2 + hstep, voffA);
;             PG8_WAIT_V(8); PG8_WAIT_L(0); PG8_BAR; PG8_MMA(0, 0, At, B0); PG8_MMA(0, 1, At, B1); PG8_BAR; PG8_SCHED;
	v_mfma_f32_16x16x32_bf16 v[60:63], v[132:135], v[180:183], v[60:63]
	v_mfma_f32_16x16x32_bf16 v[56:59], v[140:143], v[180:183], v[56:59]
	v_mfma_f32_16x16x32_bf16 v[44:47], v[132:135], v[226:229], v[44:47]
	v_mfma_f32_16x16x32_bf16 v[40:43], v[140:143], v[226:229], v[40:43]
	v_mfma_f32_16x16x32_bf16 v[28:31], v[132:135], v[234:237], v[28:31]
	v_mfma_f32_16x16x32_bf16 v[24:27], v[140:143], v[234:237], v[24:27]
	v_mfma_f32_16x16x32_bf16 v[12:15], v[132:135], v[242:245], v[12:15]
	v_mfma_f32_16x16x32_bf16 v[8:11], v[140:143], v[242:245], v[8:11]
	v_mfma_f32_16x16x32_bf16 v[60:63], v[136:139], v[222:225], v[60:63]
	v_mfma_f32_16x16x32_bf16 v[56:59], v[202:205], v[222:225], v[56:59]
	v_mfma_f32_16x16x32_bf16 v[44:47], v[136:139], v[230:233], v[44:47]
	v_mfma_f32_16x16x32_bf16 v[40:43], v[202:205], v[230:233], v[40:43]
	v_mfma_f32_16x16x32_bf16 v[28:31], v[136:139], v[238:241], v[28:31]
	v_mfma_f32_16x16x32_bf16 v[24:27], v[202:205], v[238:241], v[24:27]
	v_mfma_f32_16x16x32_bf16 v[12:15], v[136:139], v[246:249], v[12:15]
	v_mfma_f32_16x16x32_bf16 v[8:11], v[202:205], v[246:249], v[8:11]
	s_setprio 0
	s_setprio 1
	v_mfma_f32_16x16x32_bf16 v[52:55], v[206:209], v[180:183], v[52:55]
	v_mfma_f32_16x16x32_bf16 v[48:51], v[214:217], v[180:183], v[48:51]
	v_mfma_f32_16x16x32_bf16 v[36:39], v[206:209], v[226:229], v[36:39]
	v_mfma_f32_16x16x32_bf16 v[32:35], v[214:217], v[226:229], v[32:35]
	v_mfma_f32_16x16x32_bf16 v[20:23], v[206:209], v[234:237], v[20:23]
	v_mfma_f32_16x16x32_bf16 v[16:19], v[214:217], v[234:237], v[16:19]
	v_mfma_f32_16x16x32_bf16 v[4:7], v[206:209], v[242:245], v[4:7]
	v_mfma_f32_16x16x32_bf16 v[0:3], v[214:217], v[242:245], v[0:3]
	v_mfma_f32_16x16x32_bf16 v[52:55], v[210:213], v[222:225], v[52:55]
	v_mfma_f32_16x16x32_bf16 v[48:51], v[218:221], v[222:225], v[48:51]
	v_mfma_f32_16x16x32_bf16 v[36:39], v[210:213], v[230:233], v[36:39]
	v_mfma_f32_16x16x32_bf16 v[32:35], v[218:221], v[230:233], v[32:35]
	v_mfma_f32_16x16x32_bf16 v[20:23], v[210:213], v[238:241], v[20:23]
	v_mfma_f32_16x16x32_bf16 v[16:19], v[218:221], v[238:241], v[16:19]
	v_mfma_f32_16x16x32_bf16 v[4:7], v[210:213], v[246:249], v[4:7]
	v_mfma_f32_16x16x32_bf16 v[0:3], v[218:221], v[246:249], v[0:3]
	s_barrier
	s_setprio 0
	s_add_i32 s59, 0, 0x18000
	v_add_u32_e32 v144, s59, v197
	s_add_i32 s60, 0, 0x1c000
	ds_read_b128 v[132:135], v144
	ds_read_b128 v[136:139], v144 offset:1024
	ds_read_b128 v[140:143], v144 offset:2048
	ds_read_b128 v[180:183], v144 offset:3072
	v_add_u32_e32 v144, s60, v197
	ds_read_b128 v[202:205], v144
	ds_read_b128 v[206:209], v144 offset:1024
	ds_read_b128 v[210:213], v144 offset:2048
	ds_read_b128 v[214:217], v144 offset:3072
	s_add_u32 s6, s6, 0x40000
	s_addc_u32 s7, s7, 0
	s_mov_b32 m0, s27
	v_lshl_add_u64 v[190:191], s[6:7], 0, v[156:157]
	ds_read_b128 v[218:221], v199 offset:32768
	ds_read_b128 v[222:225], v199 offset:33792
	ds_read_b128 v[226:229], v199 offset:34816
	ds_read_b128 v[230:233], v199 offset:35840
	ds_read_b128 v[234:237], v199 offset:36864
	ds_read_b128 v[238:241], v199 offset:37888
	ds_read_b128 v[242:245], v199 offset:38912
	ds_read_b128 v[246:249], v199 offset:39936
	global_load_lds_dwordx4 v[190:191], off
	v_lshl_add_u64 v[190:191], s[6:7], 0, v[152:153]
	s_mov_b32 m0, s28
	s_nop 0
	global_load_lds_dwordx4 v[190:191], off
	s_waitcnt vmcnt(8)
	s_waitcnt lgkmcnt(0)
	.p2alignl 3, 3212836864
	s_setprio 1
	s_barrier
	v_mfma_f32_16x16x32_bf16 v[124:127], v[132:135], v[218:221], v[124:127]
	v_mfma_f32_16x16x32_bf16 v[120:123], v[140:143], v[218:221], v[120:123]
	v_mfma_f32_16x16x32_bf16 v[108:111], v[132:135], v[226:229], v[108:111]
	v_mfma_f32_16x16x32_bf16 v[104:107], v[140:143], v[226:229], v[104:107]
	v_mfma_f32_16x16x32_bf16 v[92:95], v[132:135], v[234:237], v[92:95]
	v_mfma_f32_16x16x32_bf16 v[88:91], v[140:143], v[234:237], v[88:91]
	v_mfma_f32_16x16x32_bf16 v[76:79], v[132:135], v[242:245], v[76:79]
	v_mfma_f32_16x16x32_bf16 v[72:75], v[140:143], v[242:245], v[72:75]
	v_mfma_f32_16x16x32_bf16 v[124:127], v[136:139], v[222:225], v[124:127]
	v_mfma_f32_16x16x32_bf16 v[120:123], v[180:183], v[222:225], v[120:123]
	v_mfma_f32_16x16x32_bf16 v[108:111], v[136:139], v[230:233], v[108:111]
	v_mfma_f32_16x16x32_bf16 v[104:107], v[180:183], v[230:233], v[104:107]
	v_mfma_f32_16x16x32_bf16 v[92:95], v[136:139], v[238:241], v[92:95]
	v_mfma_f32_16x16x32_bf16 v[88:91], v[180:183], v[238:241], v[88:91]
	v_mfma_f32_16x16x32_bf16 v[76:79], v[136:139], v[246:249], v[76:79]
	v_mfma_f32_16x16x32_bf16 v[72:75], v[180:183], v[246:249], v[72:75]
	s_setprio 0
	s_setprio 1
	v_mfma_f32_16x16x32_bf16 v[116:119], v[202:205], v[218:221], v[116:119]
	v_mfma_f32_16x16x32_bf16 v[112:115], v[210:213], v[218:221], v[112:115]
	v_mfma_f32_16x16x32_bf16 v[100:103], v[202:205], v[226:229], v[100:103]
	v_mfma_f32_16x16x32_bf16 v[96:99], v[210:213], v[226:229], v[96:99]
	v_mfma_f32_16x16x32_bf16 v[84:87], v[202:205], v[234:237], v[84:87]
	v_mfma_f32_16x16x32_bf16 v[80:83], v[210:213], v[234:237], v[80:83]
	v_mfma_f32_16x16x32_bf16 v[68:71], v[202:205], v[242:245], v[68:71]
	v_mfma_f32_16x16x32_bf16 v[64:67], v[210:213], v[242:245], v[64:67]
	v_mfma_f32_16x16x32_bf16 v[116:119], v[206:209], v[222:225], v[116:119]
	v_mfma_f32_16x16x32_bf16 v[112:115], v[214:217], v[222:225], v[112:115]
	v_mfma_f32_16x16x32_bf16 v[100:103], v[206:209], v[230:233], v[100:103]
	v_mfma_f32_16x16x32_bf16 v[96:99], v[214:217], v[230:233], v[96:99]
	v_mfma_f32_16x16x32_bf16 v[84:87], v[206:209], v[238:241], v[84:87]
	v_mfma_f32_16x16x32_bf16 v[80:83], v[214:217], v[238:241], v[80:83]
	v_mfma_f32_16x16x32_bf16 v[68:71], v[206:209], v[246:249], v[68:71]
	v_mfma_f32_16x16x32_bf16 v[64:67], v[214:217], v[246:249], v[64:67]
	s_barrier
; #define PG8_STAGE(bufoff, gbase, voff) do { _Pragma("unroll") for (int _i = 0; _i < 2; ++_i) \
;         __builtin_amdgcn_global_load_lds((const unsigned*)((const char*)(gbase) + (voff)[_i]), (PG8_LAS unsigned*)(lds + (bufoff) + ldsw + _i * 8192), 16, 0, 0); } while (0)
; #define PG8_LDA(dst, b, h) do { _Pragma("unroll") for (int m = 0; m < 4; ++m) _Pragma("unroll") for (int k = 0; k < 2; ++k) dst[m][k] = *(const PG8_LAS bf16x8*)(lds + PG8_SA(b, h) + aoff + m * 2048 + k * 1024); } while (0)
; #define PG8_MMA(ai, bj, At, Bt) do { __builtin_amdgcn_s_setprio(1); _Pragma("unroll") for (int m = 0; m < 4; ++m) _Pragma("unroll") for (int n = 0; n < 2; ++n) _Pragma("unroll") for (int k = 0; k < 2; ++k) \
;         acc[ai][bj][m][n] = __builtin_amdgcn_mfma_f32_16x16x32_bf16(Bt[n][k], At[m][k], acc[ai][bj][m][n], 0, 0, 0); __builtin_amdgcn_s_setprio(0); } while (0)
; #define PG8_WAIT_V(n) asm volatile("s_waitcnt vmcnt(" #n ")" ::: "memory")
; #define PG8_WAIT_L(n) asm volatile("s_waitcnt lgkmcnt(" #n ")" ::: "memory")
; #define PG8_BAR __builtin_amdgcn_s_barrier()
; #define PG8_SCHED __builtin_amdgcn_sched_barrier(0)
; template <class Epi, class Sched, bool ALIGN_EPI = false, bool SP2 = false>
; __device__ __forceinline__ void gemm_phase(PG8_LAS unsigned char* lds, const Gemm g, const Sched& S, const Epi& E) {
;     ...
;             PG8_LDA(At, 1, 1); PG8_STAGE(PG8_SB(1, 0), b3, voffB); PG8_STAGE(PG8_SB(1, 1), b3 + hstep, voffB); PG8_STAGE(PG8_SA(1, 0), a3, voffA);
;             PG8_WAIT_V(8); PG8_WAIT_L(0); PG8_BAR; PG8_MMA(1, 0, At, B0); PG8_MMA(1, 1, At, B1); PG8_BAR; PG8_SCHED;
	s_setprio 0
	s_add_i32 s6, s59, s24
	v_lshl_add_u64 v[172:173], v[172:173], 0, s[94:95]
	s_mov_b32 m0, s6
	ds_read_b128 v[218:221], v199 offset:49152
	ds_read_b128 v[222:225], v199 offset:50176
	ds_read_b128 v[226:229], v199 offset:51200
	ds_read_b128 v[230:233], v199 offset:52224
	ds_read_b128 v[234:237], v199 offset:53248
	ds_read_b128 v[238:241], v199 offset:54272
	ds_read_b128 v[242:245], v199 offset:55296
	ds_read_b128 v[246:249], v199 offset:56320
	global_load_lds_dwordx4 v[172:173], off
	s_add_i32 m0, s6, 0x2000
	s_add_u32 s0, s0, 0x40080
	v_lshl_add_u64 v[172:173], v[184:185], 0, s[94:95]
	s_addc_u32 s1, s1, 0
	s_add_i32 s6, s60, s24
	global_load_lds_dwordx4 v[172:173], off
	v_lshl_add_u64 v[172:173], s[0:1], 0, v[154:155]
	s_mov_b32 m0, s6
	s_nop 0
	global_load_lds_dwordx4 v[172:173], off
	v_lshl_add_u64 v[172:173], s[0:1], 0, v[150:151]
	s_add_i32 m0, s6, 0x2000
	s_nop 0
	global_load_lds_dwordx4 v[172:173], off
	v_lshl_add_u64 v[172:173], v[186:187], 0, s[94:95]
	s_mov_b32 m0, s29
	s_nop 0
	global_load_lds_dwordx4 v[172:173], off
	v_lshl_add_u64 v[172:173], v[188:189], 0, s[94:95]
	s_mov_b32 m0, s30
	s_nop 0
	global_load_lds_dwordx4 v[172:173], off
	s_waitcnt vmcnt(8)
	s_waitcnt lgkmcnt(0)
	.p2alignl 3, 3212836864
	s_setprio 1
	s_barrier
	v_mfma_f32_16x16x32_bf16 v[60:63], v[132:135], v[218:221], v[60:63]
	v_mfma_f32_16x16x32_bf16 v[56:59], v[140:143], v[218:221], v[56:59]
	v_mfma_f32_16x16x32_bf16 v[44:47], v[132:135], v[226:229], v[44:47]
	v_mfma_f32_16x16x32_bf16 v[40:43], v[140:143], v[226:229], v[40:43]
	v_mfma_f32_16x16x32_bf16 v[28:31], v[132:135], v[234:237], v[28:31]
	v_mfma_f32_16x16x32_bf16 v[24:27], v[140:143], v[234:237], v[24:27]
	v_mfma_f32_16x16x32_bf16 v[12:15], v[132:135], v[242:245], v[12:15]
	v_mfma_f32_16x16x32_bf16 v[8:11], v[140:143], v[242:245], v[8:11]
	v_mfma_f32_16x16x32_bf16 v[60:63], v[136:139], v[222:225], v[60:63]
	v_mfma_f32_16x16x32_bf16 v[56:59], v[180:183], v[222:225], v[56:59]
	v_mfma_f32_16x16x32_bf16 v[44:47], v[136:139], v[230:233], v[44:47]
	v_mfma_f32_16x16x32_bf16 v[40:43], v[180:183], v[230:233], v[40:43]
	v_mfma_f32_16x16x32_bf16 v[28:31], v[136:139], v[238:241], v[28:31]
	v_mfma_f32_16x16x32_bf16 v[24:27], v[180:183], v[238:241], v[24:27]
	v_mfma_f32_16x16x32_bf16 v[12:15], v[136:139], v[246:249], v[12:15]
	v_mfma_f32_16x16x32_bf16 v[8:11], v[180:183], v[246:249], v[8:11]
	s_setprio 0
	s_setprio 1
	v_mfma_f32_16x16x32_bf16 v[52:55], v[202:205], v[218:221], v[52:55]
	v_mfma_f32_16x16x32_bf16 v[48:51], v[210:213], v[218:221], v[48:51]
	v_mfma_f32_16x16x32_bf16 v[36:39], v[202:205], v[226:229], v[36:39]
	v_mfma_f32_16x16x32_bf16 v[32:35], v[210:213], v[226:229], v[32:35]
	v_mfma_f32_16x16x32_bf16 v[20:23], v[202:205], v[234:237], v[20:23]
	v_mfma_f32_16x16x32_bf16 v[16:19], v[210:213], v[234:237], v[16:19]
	v_mfma_f32_16x16x32_bf16 v[4:7], v[202:205], v[242:245], v[4:7]
	v_mfma_f32_16x16x32_bf16 v[0:3], v[210:213], v[242:245], v[0:3]
	v_mfma_f32_16x16x32_bf16 v[52:55], v[206:209], v[222:225], v[52:55]
	v_mfma_f32_16x16x32_bf16 v[48:51], v[214:217], v[222:225], v[48:51]
	v_mfma_f32_16x16x32_bf16 v[36:39], v[206:209], v[230:233], v[36:39]
	v_mfma_f32_16x16x32_bf16 v[32:35], v[214:217], v[230:233], v[32:35]
	v_mfma_f32_16x16x32_bf16 v[20:23], v[206:209], v[238:241], v[20:23]
	v_mfma_f32_16x16x32_bf16 v[16:19], v[214:217], v[238:241], v[16:19]
	v_mfma_f32_16x16x32_bf16 v[4:7], v[206:209], v[246:249], v[4:7]
	v_mfma_f32_16x16x32_bf16 v[0:3], v[214:217], v[246:249], v[0:3]
	s_barrier
	s_setprio 0
	s_add_i32 s58, s58, 2
	s_add_u32 s4, s4, 0x100
	s_addc_u32 s5, s5, 0
	s_add_u32 s56, s56, 0x100
	s_addc_u32 s57, s57, 0
	s_cmp_gt_u32 s58, 13
	s_cbranch_scc1 .LBB0_247

; #define PG8_STAGE(bufoff, gbase, voff) do { _Pragma("unroll") for (int _i = 0; _i < 2; ++_i) \
;         __builtin_amdgcn_global_load_lds((const unsigned*)((const char*)(gbase) + (voff)[_i]), (PG8_LAS unsigned*)(lds + (bufoff) + ldsw + _i * 8192), 16, 0, 0); } while (0)
; #define PG8_LDA(dst, b, h) do { _Pragma("unroll") for (int m = 0; m < 4; ++m) _Pragma("unroll") for (int k = 0; k < 2; ++k) dst[m][k] = *(const PG8_LAS bf16x8*)(lds + PG8_SA(b, h) + aoff + m * 2048 + k * 1024); } while (0)
; #define PG8_LDB(dst, b, h) do { _Pragma("unroll") for (int n = 0; n < 2; ++n) _Pragma("unroll") for (int k = 0; k < 2; ++k) dst[n][k] = *(const PG8_LAS bf16x8*)(lds + PG8_SB(b, h) + boff + n * 2048 + k * 1024); } while (0)
; #define PG8_MMA(ai, bj, At, Bt) do { __builtin_amdgcn_s_setprio(1); _Pragma("unroll") for (int m = 0; m < 4; ++m) _Pragma("unroll") for (int n = 0; n < 2; ++n) _Pragma("unroll") for (int k = 0; k < 2; ++k) \
;         acc[ai][bj][m][n] = __builtin_amdgcn_mfma_f32_16x16x32_bf16(Bt[n][k], At[m][k], acc[ai][bj][m][n], 0, 0, 0); __builtin_amdgcn_s_setprio(0); } while (0)
; #define PG8_WAIT_V(n) asm volatile("s_waitcnt vmcnt(" #n ")" ::: "memory")
; #define PG8_BAR __builtin_amdgcn_s_barrier()
; template <class Epi, class Sched, bool ALIGN_EPI = false, bool SP2 = false>
; __device__ __forceinline__ void gemm_phase(PG8_LAS unsigned char* lds, const Gemm g, const Sched& S, const Epi& E) {
;     ...
;             const bool last = (t == nt - 2);
;             const char* a1 = cA + (size_t)(t + 1) * kstep;
;             const char* a2 = last ? nA : cA + (size_t)(t + 2) * kstep; const char* b2 = last ? nB : cB + (size_t)(t + 2) * kstep;
;             const char* a3 = a2 + kstep; const char* b3 = b2 + kstep;
;             if (last && has_next) S.a_ready(nxt);
;             if (last) E.pre(cur, wid, lane);
;             if constexpr (SP2) {
;             PG8_LDB(B0, 0, 0); PG8_LDB(B1, 0, 1); PG8_SCHED; PG8_LDA(At, 0, 0); PG8_STAGE(PG8_SA(1, 1), a1 + hstep, voffA);
;             PG8_WAIT_V(8); PG8_WAIT_L(0); PG8_BAR; PG8_MMA(0, 0, At, B0); PG8_MMA(0, 1, At, B1); PG8_BAR; PG8_SCHED;
;             PG8_LDA(At, 0, 1); PG8_STAGE(PG8_SB(0, 0), b2, voffB); PG8_STAGE(PG8_SB(0, 1), b2 + hstep, voffB); PG8_STAGE(PG8_SA(0, 0), a2, voffA);
;             PG8_WAIT_V(8); PG8_WAIT_L(0); PG8_BAR; PG8_MMA(1, 0, At, B0); PG8_MMA(1, 1, At, B1); PG8_BAR; PG8_SCHED;
.LBB0_1562:
	s_add_u32 s0, s28, 0xfffc0080
	s_addc_u32 s1, s29, -1
	s_add_i32 s58, 0, 0x10000
	s_cmp_eq_u32 s57, 12
	s_cselect_b32 s7, s47, s1
	s_cselect_b32 s6, s53, s0
	s_cselect_b32 s1, s45, s56
	s_cselect_b32 s0, s54, s55
	s_add_i32 s60, 0, 0x14000
	v_add_u32_e32 v160, s58, v143
	v_add_u32_e32 v172, s60, v143
	ds_read_b128 v[138:141], v160
	ds_read_b128 v[152:155], v160 offset:1024
	ds_read_b128 v[156:159], v160 offset:2048
	ds_read_b128 v[160:163], v160 offset:3072
	ds_read_b128 v[164:167], v172
	ds_read_b128 v[168:171], v172 offset:1024
	ds_read_b128 v[180:183], v172 offset:2048
	ds_read_b128 v[198:201], v172 offset:3072
	v_lshl_add_u64 v[172:173], s[28:29], 0, v[134:135]
	s_add_i32 m0, s26, 0xc000
	ds_read_b128 v[202:205], v151
	ds_read_b128 v[206:209], v151 offset:1024
	ds_read_b128 v[210:213], v151 offset:2048
	ds_read_b128 v[214:217], v151 offset:3072
	ds_read_b128 v[218:221], v151 offset:4096
	ds_read_b128 v[222:225], v151 offset:5120
	ds_read_b128 v[226:229], v151 offset:6144
	ds_read_b128 v[230:233], v151 offset:7168
	global_load_lds_dwordx4 v[172:173], off
	v_lshl_add_u64 v[172:173], s[28:29], 0, v[136:137]
	s_add_i32 m0, s26, 0xe000
	s_nop 0
	global_load_lds_dwordx4 v[172:173], off
	s_waitcnt vmcnt(8)
	s_waitcnt lgkmcnt(0)
	.p2alignl 3, 3212836864
	s_setprio 1
	s_barrier
	v_mfma_f32_16x16x32_bf16 v[120:123], v[138:141], v[202:205], v[120:123]
	v_mfma_f32_16x16x32_bf16 v[124:127], v[156:159], v[202:205], v[124:127]
	v_mfma_f32_16x16x32_bf16 v[100:103], v[138:141], v[210:213], v[100:103]
	v_mfma_f32_16x16x32_bf16 v[104:107], v[156:159], v[210:213], v[104:107]
	v_mfma_f32_16x16x32_bf16 v[84:87], v[138:141], v[218:221], v[84:87]
	v_mfma_f32_16x16x32_bf16 v[88:91], v[156:159], v[218:221], v[88:91]
	v_mfma_f32_16x16x32_bf16 v[68:71], v[138:141], v[226:229], v[68:71]
	v_mfma_f32_16x16x32_bf16 v[72:75], v[156:159], v[226:229], v[72:75]
	v_mfma_f32_16x16x32_bf16 v[120:123], v[152:155], v[206:209], v[120:123]
	v_mfma_f32_16x16x32_bf16 v[124:127], v[160:163], v[206:209], v[124:127]
	v_mfma_f32_16x16x32_bf16 v[100:103], v[152:155], v[214:217], v[100:103]
	v_mfma_f32_16x16x32_bf16 v[104:107], v[160:163], v[214:217], v[104:107]
	v_mfma_f32_16x16x32_bf16 v[84:87], v[152:155], v[222:225], v[84:87]
	v_mfma_f32_16x16x32_bf16 v[88:91], v[160:163], v[222:225], v[88:91]
	v_mfma_f32_16x16x32_bf16 v[68:71], v[152:155], v[230:233], v[68:71]
	v_mfma_f32_16x16x32_bf16 v[72:75], v[160:163], v[230:233], v[72:75]
	s_setprio 0
	s_setprio 1
	v_mfma_f32_16x16x32_bf16 v[112:115], v[164:167], v[202:205], v[112:115]
	v_mfma_f32_16x16x32_bf16 v[116:119], v[180:183], v[202:205], v[116:119]
	v_mfma_f32_16x16x32_bf16 v[96:99], v[164:167], v[210:213], v[96:99]
	v_mfma_f32_16x16x32_bf16 v[108:111], v[180:183], v[210:213], v[108:111]
	v_mfma_f32_16x16x32_bf16 v[80:83], v[164:167], v[218:221], v[80:83]
	v_mfma_f32_16x16x32_bf16 v[92:95], v[180:183], v[218:221], v[92:95]
	v_mfma_f32_16x16x32_bf16 v[64:67], v[164:167], v[226:229], v[64:67]
	v_mfma_f32_16x16x32_bf16 v[76:79], v[180:183], v[226:229], v[76:79]
	v_mfma_f32_16x16x32_bf16 v[112:115], v[168:171], v[206:209], v[112:115]
	v_mfma_f32_16x16x32_bf16 v[116:119], v[198:201], v[206:209], v[116:119]
	v_mfma_f32_16x16x32_bf16 v[96:99], v[168:171], v[214:217], v[96:99]
	v_mfma_f32_16x16x32_bf16 v[108:111], v[198:201], v[214:217], v[108:111]
	v_mfma_f32_16x16x32_bf16 v[80:83], v[168:171], v[222:225], v[80:83]
	v_mfma_f32_16x16x32_bf16 v[92:95], v[198:201], v[222:225], v[92:95]
	v_mfma_f32_16x16x32_bf16 v[64:67], v[168:171], v[230:233], v[64:67]
	v_mfma_f32_16x16x32_bf16 v[76:79], v[198:201], v[230:233], v[76:79]
	s_barrier
	s_setprio 0
	s_add_i32 s58, s58, s25
	v_lshl_add_u64 v[172:173], s[0:1], 0, v[144:145]
	s_mov_b32 m0, s58
	ds_read_b128 v[202:205], v151 offset:16384
	ds_read_b128 v[206:209], v151 offset:17408
	ds_read_b128 v[210:213], v151 offset:18432
	ds_read_b128 v[214:217], v151 offset:19456
	ds_read_b128 v[218:221], v151 offset:20480
	ds_read_b128 v[222:225], v151 offset:21504
	ds_read_b128 v[226:229], v151 offset:22528
	ds_read_b128 v[230:233], v151 offset:23552
	global_load_lds_dwordx4 v[172:173], off
	s_add_i32 m0, s58, 0x2000
	s_add_u32 s58, s0, 0x40000
	v_lshl_add_u64 v[184:185], s[0:1], 0, v[128:129]
	s_addc_u32 s59, s1, 0
	s_add_i32 s60, s60, s25
	global_load_lds_dwordx4 v[184:185], off
	v_lshl_add_u64 v[186:187], s[58:59], 0, v[144:145]
	s_mov_b32 m0, s60
	v_lshl_add_u64 v[188:189], s[6:7], 0, v[130:131]
	global_load_lds_dwordx4 v[186:187], off
	v_lshl_add_u64 v[186:187], s[58:59], 0, v[128:129]
	s_add_i32 m0, s60, 0x2000
	s_nop 0
	global_load_lds_dwordx4 v[186:187], off
	v_lshl_add_u64 v[186:187], s[6:7], 0, v[132:133]
	s_mov_b32 m0, s26
	s_nop 0
	global_load_lds_dwordx4 v[186:187], off
	s_mov_b32 m0, s27
	s_nop 0
	global_load_lds_dwordx4 v[188:189], off
	s_waitcnt vmcnt(8)
	s_waitcnt lgkmcnt(0)
	.p2alignl 3, 3212836864
	s_setprio 1
	s_barrier
; #define PG8_STAGE(bufoff, gbase, voff) do { _Pragma("unroll") for (int _i = 0; _i < 2; ++_i) \
;         __builtin_amdgcn_global_load_lds((const unsigned*)((const char*)(gbase) + (voff)[_i]), (PG8_LAS unsigned*)(lds + (bufoff) + ldsw + _i * 8192), 16, 0, 0); } while (0)
; #define PG8_LDA(dst, b, h) do { _Pragma("unroll") for (int m = 0; m < 4; ++m) _Pragma("unroll") for (int k = 0; k < 2; ++k) dst[m][k] = *(const PG8_LAS bf16x8*)(lds + PG8_SA(b, h) + aoff + m * 2048 + k * 1024); } while (0)
; #define PG8_LDB(dst, b, h) do { _Pragma("unroll") for (int n = 0; n < 2; ++n) _Pragma("unroll") for (int k = 0; k < 2; ++k) dst[n][k] = *(const PG8_LAS bf16x8*)(lds + PG8_SB(b, h) + boff + n * 2048 + k * 1024); } while (0)
; #define PG8_MMA(ai, bj, At, Bt) do { __builtin_amdgcn_s_setprio(1); _Pragma("unroll") for (int m = 0; m < 4; ++m) _Pragma("unroll") for (int n = 0; n < 2; ++n) _Pragma("unroll") for (int k = 0; k < 2; ++k) \
;         acc[ai][bj][m][n] = __builtin_amdgcn_mfma_f32_16x16x32_bf16(Bt[n][k], At[m][k], acc[ai][bj][m][n], 0, 0, 0); __builtin_amdgcn_s_setprio(0); } while (0)
; #define PG8_WAIT_V(n) asm volatile("s_waitcnt vmcnt(" #n ")" ::: "memory")
; #define PG8_WAIT_L(n) asm volatile("s_waitcnt lgkmcnt(" #n ")" ::: "memory")
; #define PG8_BAR __builtin_amdgcn_s_barrier()
; #define PG8_SCHED __builtin_amdgcn_sched_barrier(0)
; template <class Epi, class Sched, bool ALIGN_EPI = false, bool SP2 = false>
; __device__ __forceinline__ void gemm_phase(PG8_LAS unsigned char* lds, const Gemm g, const Sched& S, const Epi& E) {
;     ...
;             PG8_WAIT_V(8); PG8_WAIT_L(0); PG8_BAR; PG8_MMA(1, 0, At, B0); PG8_MMA(1, 1, At, B1); PG8_BAR; PG8_SCHED;
;             PG8_LDB(B0, 1, 0); PG8_LDB(B1, 1, 1); PG8_SCHED; PG8_LDA(At, 1, 0); PG8_STAGE(PG8_SA(0, 1), a2 + hstep, voffA);
;             PG8_WAIT_V(8); PG8_WAIT_L(0); PG8_BAR; PG8_MMA(0, 0, At, B0); PG8_MMA(0, 1, At, B1); PG8_BAR; PG8_SCHED;
	v_mfma_f32_16x16x32_bf16 v[52:55], v[138:141], v[202:205], v[52:55]
	v_mfma_f32_16x16x32_bf16 v[56:59], v[156:159], v[202:205], v[56:59]
	v_mfma_f32_16x16x32_bf16 v[36:39], v[138:141], v[210:213], v[36:39]
	v_mfma_f32_16x16x32_bf16 v[40:43], v[156:159], v[210:213], v[40:43]
	v_mfma_f32_16x16x32_bf16 v[20:23], v[138:141], v[218:221], v[20:23]
	v_mfma_f32_16x16x32_bf16 v[24:27], v[156:159], v[218:221], v[24:27]
	v_mfma_f32_16x16x32_bf16 v[4:7], v[138:141], v[226:229], v[4:7]
	v_mfma_f32_16x16x32_bf16 v[8:11], v[156:159], v[226:229], v[8:11]
	v_mfma_f32_16x16x32_bf16 v[52:55], v[152:155], v[206:209], v[52:55]
	v_mfma_f32_16x16x32_bf16 v[56:59], v[160:163], v[206:209], v[56:59]
	v_mfma_f32_16x16x32_bf16 v[36:39], v[152:155], v[214:217], v[36:39]
	v_mfma_f32_16x16x32_bf16 v[40:43], v[160:163], v[214:217], v[40:43]
	v_mfma_f32_16x16x32_bf16 v[20:23], v[152:155], v[222:225], v[20:23]
	v_mfma_f32_16x16x32_bf16 v[24:27], v[160:163], v[222:225], v[24:27]
	v_mfma_f32_16x16x32_bf16 v[4:7], v[152:155], v[230:233], v[4:7]
	v_mfma_f32_16x16x32_bf16 v[8:11], v[160:163], v[230:233], v[8:11]
	s_setprio 0
	s_setprio 1
	v_mfma_f32_16x16x32_bf16 v[48:51], v[164:167], v[202:205], v[48:51]
	v_mfma_f32_16x16x32_bf16 v[60:63], v[180:183], v[202:205], v[60:63]
	v_mfma_f32_16x16x32_bf16 v[32:35], v[164:167], v[210:213], v[32:35]
	v_mfma_f32_16x16x32_bf16 v[44:47], v[180:183], v[210:213], v[44:47]
	v_mfma_f32_16x16x32_bf16 v[16:19], v[164:167], v[218:221], v[16:19]
	v_mfma_f32_16x16x32_bf16 v[28:31], v[180:183], v[218:221], v[28:31]
	v_mfma_f32_16x16x32_bf16 v[0:3], v[164:167], v[226:229], v[0:3]
	v_mfma_f32_16x16x32_bf16 v[12:15], v[180:183], v[226:229], v[12:15]
	v_mfma_f32_16x16x32_bf16 v[48:51], v[168:171], v[206:209], v[48:51]
	v_mfma_f32_16x16x32_bf16 v[60:63], v[198:201], v[206:209], v[60:63]
	v_mfma_f32_16x16x32_bf16 v[32:35], v[168:171], v[214:217], v[32:35]
	v_mfma_f32_16x16x32_bf16 v[44:47], v[198:201], v[214:217], v[44:47]
	v_mfma_f32_16x16x32_bf16 v[16:19], v[168:171], v[222:225], v[16:19]
	v_mfma_f32_16x16x32_bf16 v[28:31], v[198:201], v[222:225], v[28:31]
	v_mfma_f32_16x16x32_bf16 v[0:3], v[168:171], v[230:233], v[0:3]
	v_mfma_f32_16x16x32_bf16 v[12:15], v[198:201], v[230:233], v[12:15]
	s_barrier
	s_setprio 0
	s_add_i32 s58, 0, 0x18000
	s_add_i32 s59, 0, 0x1c000
	v_add_u32_e32 v160, s58, v143
	v_add_u32_e32 v190, s59, v143
	ds_read_b128 v[138:141], v160
	ds_read_b128 v[152:155], v160 offset:1024
	ds_read_b128 v[156:159], v160 offset:2048
	ds_read_b128 v[160:163], v160 offset:3072
	ds_read_b128 v[164:167], v190
	ds_read_b128 v[168:171], v190 offset:1024
	ds_read_b128 v[180:183], v190 offset:2048
	ds_read_b128 v[198:201], v190 offset:3072
	s_add_u32 s6, s6, 0x40000
	s_addc_u32 s7, s7, 0
	s_mov_b32 m0, s30
	v_lshl_add_u64 v[190:191], s[6:7], 0, v[132:133]
	ds_read_b128 v[202:205], v151 offset:32768
	ds_read_b128 v[206:209], v151 offset:33792
	ds_read_b128 v[210:213], v151 offset:34816
	ds_read_b128 v[214:217], v151 offset:35840
	ds_read_b128 v[218:221], v151 offset:36864
	ds_read_b128 v[222:225], v151 offset:37888
	ds_read_b128 v[226:229], v151 offset:38912
	ds_read_b128 v[230:233], v151 offset:39936
	global_load_lds_dwordx4 v[190:191], off
	v_lshl_add_u64 v[190:191], s[6:7], 0, v[130:131]
	s_mov_b32 m0, s31
	s_nop 0
	global_load_lds_dwordx4 v[190:191], off
	s_waitcnt vmcnt(8)
	s_waitcnt lgkmcnt(0)
	.p2alignl 3, 3212836864
	s_setprio 1
	s_barrier
	v_mfma_f32_16x16x32_bf16 v[120:123], v[138:141], v[202:205], v[120:123]
	v_mfma_f32_16x16x32_bf16 v[124:127], v[156:159], v[202:205], v[124:127]
	v_mfma_f32_16x16x32_bf16 v[100:103], v[138:141], v[210:213], v[100:103]
	v_mfma_f32_16x16x32_bf16 v[104:107], v[156:159], v[210:213], v[104:107]
	v_mfma_f32_16x16x32_bf16 v[84:87], v[138:141], v[218:221], v[84:87]
	v_mfma_f32_16x16x32_bf16 v[88:91], v[156:159], v[218:221], v[88:91]
	v_mfma_f32_16x16x32_bf16 v[68:71], v[138:141], v[226:229], v[68:71]
	v_mfma_f32_16x16x32_bf16 v[72:75], v[156:159], v[226:229], v[72:75]
	v_mfma_f32_16x16x32_bf16 v[120:123], v[152:155], v[206:209], v[120:123]
	v_mfma_f32_16x16x32_bf16 v[124:127], v[160:163], v[206:209], v[124:127]
	v_mfma_f32_16x16x32_bf16 v[100:103], v[152:155], v[214:217], v[100:103]
	v_mfma_f32_16x16x32_bf16 v[104:107], v[160:163], v[214:217], v[104:107]
	v_mfma_f32_16x16x32_bf16 v[84:87], v[152:155], v[222:225], v[84:87]
	v_mfma_f32_16x16x32_bf16 v[88:91], v[160:163], v[222:225], v[88:91]
	v_mfma_f32_16x16x32_bf16 v[68:71], v[152:155], v[230:233], v[68:71]
	v_mfma_f32_16x16x32_bf16 v[72:75], v[160:163], v[230:233], v[72:75]
	s_setprio 0
	s_setprio 1
	v_mfma_f32_16x16x32_bf16 v[112:115], v[164:167], v[202:205], v[112:115]
	v_mfma_f32_16x16x32_bf16 v[116:119], v[180:183], v[202:205], v[116:119]
	v_mfma_f32_16x16x32_bf16 v[96:99], v[164:167], v[210:213], v[96:99]
	v_mfma_f32_16x16x32_bf16 v[108:111], v[180:183], v[210:213], v[108:111]
	v_mfma_f32_16x16x32_bf16 v[80:83], v[164:167], v[218:221], v[80:83]
	v_mfma_f32_16x16x32_bf16 v[92:95], v[180:183], v[218:221], v[92:95]
	v_mfma_f32_16x16x32_bf16 v[64:67], v[164:167], v[226:229], v[64:67]
	v_mfma_f32_16x16x32_bf16 v[76:79], v[180:183], v[226:229], v[76:79]
	v_mfma_f32_16x16x32_bf16 v[112:115], v[168:171], v[206:209], v[112:115]
	v_mfma_f32_16x16x32_bf16 v[116:119], v[198:201], v[206:209], v[116:119]
	v_mfma_f32_16x16x32_bf16 v[96:99], v[168:171], v[214:217], v[96:99]
	v_mfma_f32_16x16x32_bf16 v[108:111], v[198:201], v[214:217], v[108:111]
	v_mfma_f32_16x16x32_bf16 v[80:83], v[168:171], v[222:225], v[80:83]
	v_mfma_f32_16x16x32_bf16 v[92:95], v[198:201], v[222:225], v[92:95]
	v_mfma_f32_16x16x32_bf16 v[64:67], v[168:171], v[230:233], v[64:67]
	v_mfma_f32_16x16x32_bf16 v[76:79], v[198:201], v[230:233], v[76:79]
	s_barrier
; #define PG8_STAGE(bufoff, gbase, voff) do { _Pragma("unroll") for (int _i = 0; _i < 2; ++_i) \
;         __builtin_amdgcn_global_load_lds((const unsigned*)((const char*)(gbase) + (voff)[_i]), (PG8_LAS unsigned*)(lds + (bufoff) + ldsw + _i * 8192), 16, 0, 0); } while (0)
; #define PG8_LDA(dst, b, h) do { _Pragma("unroll") for (int m = 0; m < 4; ++m) _Pragma("unroll") for (int k = 0; k < 2; ++k) dst[m][k] = *(const PG8_LAS bf16x8*)(lds + PG8_SA(b, h) + aoff + m * 2048 + k * 1024); } while (0)
; #define PG8_MMA(ai, bj, At, Bt) do { __builtin_amdgcn_s_setprio(1); _Pragma("unroll") for (int m = 0; m < 4; ++m) _Pragma("unroll") for (int n = 0; n < 2; ++n) _Pragma("unroll") for (int k = 0; k < 2; ++k) \
;         acc[ai][bj][m][n] = __builtin_amdgcn_mfma_f32_16x16x32_bf16(Bt[n][k], At[m][k], acc[ai][bj][m][n], 0, 0, 0); __builtin_amdgcn_s_setprio(0); } while (0)
; #define PG8_WAIT_V(n) asm volatile("s_waitcnt vmcnt(" #n ")" ::: "memory")
; #define PG8_WAIT_L(n) asm volatile("s_waitcnt lgkmcnt(" #n ")" ::: "memory")
; #define PG8_BAR __builtin_amdgcn_s_barrier()
; #define PG8_SCHED __builtin_amdgcn_sched_barrier(0)
; template <class Epi, class Sched, bool ALIGN_EPI = false, bool SP2 = false>
; __device__ __forceinline__ void gemm_phase(PG8_LAS unsigned char* lds, const Gemm g, const Sched& S, const Epi& E) {
;     ...
;             PG8_LDA(At, 1, 1); PG8_STAGE(PG8_SB(1, 0), b3, voffB); PG8_STAGE(PG8_SB(1, 1), b3 + hstep, voffB); PG8_STAGE(PG8_SA(1, 0), a3, voffA);
;             PG8_WAIT_V(8); PG8_WAIT_L(0); PG8_BAR; PG8_MMA(1, 0, At, B0); PG8_MMA(1, 1, At, B1); PG8_BAR; PG8_SCHED;
;     ...
;         if constexpr (ALIGN_EPI) { if (wr == 0) PG8_BAR; }
	s_setprio 0
	s_add_i32 s6, s58, s25
	v_lshl_add_u64 v[172:173], v[172:173], 0, s[94:95]
	s_mov_b32 m0, s6
	ds_read_b128 v[202:205], v151 offset:49152
	ds_read_b128 v[206:209], v151 offset:50176
	ds_read_b128 v[210:213], v151 offset:51200
	ds_read_b128 v[214:217], v151 offset:52224
	ds_read_b128 v[218:221], v151 offset:53248
	ds_read_b128 v[222:225], v151 offset:54272
	ds_read_b128 v[226:229], v151 offset:55296
	ds_read_b128 v[230:233], v151 offset:56320
	global_load_lds_dwordx4 v[172:173], off
	s_add_i32 m0, s6, 0x2000
	s_add_u32 s0, s0, 0x40080
	v_lshl_add_u64 v[172:173], v[184:185], 0, s[94:95]
	s_addc_u32 s1, s1, 0
	s_add_i32 s6, s59, s25
	global_load_lds_dwordx4 v[172:173], off
	v_lshl_add_u64 v[172:173], s[0:1], 0, v[144:145]
	s_mov_b32 m0, s6
	s_nop 0
	global_load_lds_dwordx4 v[172:173], off
	v_lshl_add_u64 v[172:173], s[0:1], 0, v[128:129]
	s_add_i32 m0, s6, 0x2000
	s_nop 0
	global_load_lds_dwordx4 v[172:173], off
	v_lshl_add_u64 v[172:173], v[186:187], 0, s[94:95]
	s_mov_b32 m0, s34
	s_nop 0
	global_load_lds_dwordx4 v[172:173], off
	v_lshl_add_u64 v[172:173], v[188:189], 0, s[94:95]
	s_mov_b32 m0, s35
	s_nop 0
	global_load_lds_dwordx4 v[172:173], off
	s_waitcnt vmcnt(8)
	s_waitcnt lgkmcnt(0)
	.p2alignl 3, 3212836864
	s_setprio 1
	s_barrier
	v_mfma_f32_16x16x32_bf16 v[52:55], v[138:141], v[202:205], v[52:55]
	v_mfma_f32_16x16x32_bf16 v[56:59], v[156:159], v[202:205], v[56:59]
	v_mfma_f32_16x16x32_bf16 v[36:39], v[138:141], v[210:213], v[36:39]
	v_mfma_f32_16x16x32_bf16 v[40:43], v[156:159], v[210:213], v[40:43]
	v_mfma_f32_16x16x32_bf16 v[20:23], v[138:141], v[218:221], v[20:23]
	v_mfma_f32_16x16x32_bf16 v[24:27], v[156:159], v[218:221], v[24:27]
	v_mfma_f32_16x16x32_bf16 v[4:7], v[138:141], v[226:229], v[4:7]
	v_mfma_f32_16x16x32_bf16 v[8:11], v[156:159], v[226:229], v[8:11]
	v_mfma_f32_16x16x32_bf16 v[52:55], v[152:155], v[206:209], v[52:55]
	v_mfma_f32_16x16x32_bf16 v[56:59], v[160:163], v[206:209], v[56:59]
	v_mfma_f32_16x16x32_bf16 v[36:39], v[152:155], v[214:217], v[36:39]
	v_mfma_f32_16x16x32_bf16 v[40:43], v[160:163], v[214:217], v[40:43]
	v_mfma_f32_16x16x32_bf16 v[20:23], v[152:155], v[222:225], v[20:23]
	v_mfma_f32_16x16x32_bf16 v[24:27], v[160:163], v[222:225], v[24:27]
	v_mfma_f32_16x16x32_bf16 v[4:7], v[152:155], v[230:233], v[4:7]
	v_mfma_f32_16x16x32_bf16 v[8:11], v[160:163], v[230:233], v[8:11]
	s_setprio 0
	s_setprio 1
	v_mfma_f32_16x16x32_bf16 v[48:51], v[164:167], v[202:205], v[48:51]
	v_mfma_f32_16x16x32_bf16 v[60:63], v[180:183], v[202:205], v[60:63]
	v_mfma_f32_16x16x32_bf16 v[32:35], v[164:167], v[210:213], v[32:35]
	v_mfma_f32_16x16x32_bf16 v[44:47], v[180:183], v[210:213], v[44:47]
	v_mfma_f32_16x16x32_bf16 v[16:19], v[164:167], v[218:221], v[16:19]
	v_mfma_f32_16x16x32_bf16 v[28:31], v[180:183], v[218:221], v[28:31]
	v_mfma_f32_16x16x32_bf16 v[0:3], v[164:167], v[226:229], v[0:3]
	v_mfma_f32_16x16x32_bf16 v[12:15], v[180:183], v[226:229], v[12:15]
	v_mfma_f32_16x16x32_bf16 v[48:51], v[168:171], v[206:209], v[48:51]
	v_mfma_f32_16x16x32_bf16 v[60:63], v[198:201], v[206:209], v[60:63]
	v_mfma_f32_16x16x32_bf16 v[32:35], v[168:171], v[214:217], v[32:35]
	v_mfma_f32_16x16x32_bf16 v[44:47], v[198:201], v[214:217], v[44:47]
	v_mfma_f32_16x16x32_bf16 v[16:19], v[168:171], v[222:225], v[16:19]
	v_mfma_f32_16x16x32_bf16 v[28:31], v[198:201], v[222:225], v[28:31]
	v_mfma_f32_16x16x32_bf16 v[0:3], v[168:171], v[230:233], v[0:3]
	v_mfma_f32_16x16x32_bf16 v[12:15], v[198:201], v[230:233], v[12:15]
	s_barrier
	s_setprio 0
	s_add_i32 s57, s57, 2
	s_add_u32 s28, s28, 0x100
	s_addc_u32 s29, s29, 0
	s_add_u32 s55, s55, 0x100
	s_addc_u32 s56, s56, 0
	s_cmp_gt_u32 s57, 13
	s_cbranch_scc0 .LBB0_1562
	s_and_b64 vcc, exec, s[42:43]
	s_cbranch_vccz .LBB0_1565
	s_barrier

; #define PG8_STAGE(bufoff, gbase, voff) do { _Pragma("unroll") for (int _i = 0; _i < 2; ++_i) \
;         __builtin_amdgcn_global_load_lds((const unsigned*)((const char*)(gbase) + (voff)[_i]), (PG8_LAS unsigned*)(lds + (bufoff) + ldsw + _i * 8192), 16, 0, 0); } while (0)
; #define PG8_LDA(dst, b, h) do { _Pragma("unroll") for (int m = 0; m < 4; ++m) _Pragma("unroll") for (int k = 0; k < 2; ++k) dst[m][k] = *(const PG8_LAS bf16x8*)(lds + PG8_SA(b, h) + aoff + m * 2048 + k * 1024); } while (0)
; #define PG8_MMA(ai, bj, At, Bt) do { __builtin_amdgcn_s_setprio(1); _Pragma("unroll") for (int m = 0; m < 4; ++m) _Pragma("unroll") for (int n = 0; n < 2; ++n) _Pragma("unroll") for (int k = 0; k < 2; ++k) \
;         acc[ai][bj][m][n] = __builtin_amdgcn_mfma_f32_16x16x32_bf16(Bt[n][k], At[m][k], acc[ai][bj][m][n], 0, 0, 0); __builtin_amdgcn_s_setprio(0); } while (0)
; #define PG8_WAIT_V(n) asm volatile("s_waitcnt vmcnt(" #n ")" ::: "memory")
; #define PG8_WAIT_L(n) asm volatile("s_waitcnt lgkmcnt(" #n ")" ::: "memory")
; #define PG8_BAR __builtin_amdgcn_s_barrier()
; #define PG8_SCHED __builtin_amdgcn_sched_barrier(0)
; template <class Epi, class Sched, bool ALIGN_EPI = false, bool SP2 = false>
; __device__ __forceinline__ void gemm_phase(PG8_LAS unsigned char* lds, const Gemm g, const Sched& S, const Epi& E) {
;     ...
;             PG8_WAIT_V(8); PG8_WAIT_L(0); PG8_BAR; PG8_MMA(0, 0, At, B0); PG8_MMA(0, 1, At, B1); PG8_BAR; PG8_SCHED;
;             PG8_LDA(At, 0, 1); PG8_STAGE(PG8_SB(0, 0), b2, voffB); PG8_STAGE(PG8_SB(0, 1), b2 + hstep, voffB); PG8_STAGE(PG8_SA(0, 0), a2, voffA);
;             PG8_WAIT_V(8); PG8_WAIT_L(0); PG8_BAR; PG8_MMA(1, 0, At, B0); PG8_MMA(1, 1, At, B1); PG8_BAR; PG8_SCHED;
.Lgu_relaxed0:
	s_waitcnt lgkmcnt(0)
	.p2alignl 3, 3212836864
	s_setprio 1
	s_barrier
	v_mfma_f32_16x16x32_bf16 v[124:127], v[132:135], v[216:219], v[124:127]
	v_mfma_f32_16x16x32_bf16 v[116:119], v[140:143], v[216:219], v[116:119]
	v_mfma_f32_16x16x32_bf16 v[108:111], v[132:135], v[224:227], v[108:111]
	v_mfma_f32_16x16x32_bf16 v[100:103], v[140:143], v[224:227], v[100:103]
	v_mfma_f32_16x16x32_bf16 v[92:95], v[132:135], v[232:235], v[92:95]
	v_mfma_f32_16x16x32_bf16 v[84:87], v[140:143], v[232:235], v[84:87]
	v_mfma_f32_16x16x32_bf16 v[76:79], v[132:135], v[240:243], v[76:79]
	v_mfma_f32_16x16x32_bf16 v[68:71], v[140:143], v[240:243], v[68:71]
	v_mfma_f32_16x16x32_bf16 v[124:127], v[136:139], v[220:223], v[124:127]
	v_mfma_f32_16x16x32_bf16 v[116:119], v[180:183], v[220:223], v[116:119]
	v_mfma_f32_16x16x32_bf16 v[108:111], v[136:139], v[228:231], v[108:111]
	v_mfma_f32_16x16x32_bf16 v[100:103], v[180:183], v[228:231], v[100:103]
	v_mfma_f32_16x16x32_bf16 v[92:95], v[136:139], v[236:239], v[92:95]
	v_mfma_f32_16x16x32_bf16 v[84:87], v[180:183], v[236:239], v[84:87]
	v_mfma_f32_16x16x32_bf16 v[76:79], v[136:139], v[244:247], v[76:79]
	v_mfma_f32_16x16x32_bf16 v[68:71], v[180:183], v[244:247], v[68:71]
	s_setprio 0
	s_setprio 1
	v_mfma_f32_16x16x32_bf16 v[120:123], v[200:203], v[216:219], v[120:123]
	v_mfma_f32_16x16x32_bf16 v[112:115], v[208:211], v[216:219], v[112:115]
	v_mfma_f32_16x16x32_bf16 v[104:107], v[200:203], v[224:227], v[104:107]
	v_mfma_f32_16x16x32_bf16 v[96:99], v[208:211], v[224:227], v[96:99]
	v_mfma_f32_16x16x32_bf16 v[88:91], v[200:203], v[232:235], v[88:91]
	v_mfma_f32_16x16x32_bf16 v[80:83], v[208:211], v[232:235], v[80:83]
	v_mfma_f32_16x16x32_bf16 v[72:75], v[200:203], v[240:243], v[72:75]
	v_mfma_f32_16x16x32_bf16 v[64:67], v[208:211], v[240:243], v[64:67]
	v_mfma_f32_16x16x32_bf16 v[120:123], v[204:207], v[220:223], v[120:123]
	v_mfma_f32_16x16x32_bf16 v[112:115], v[212:215], v[220:223], v[112:115]
	v_mfma_f32_16x16x32_bf16 v[104:107], v[204:207], v[228:231], v[104:107]
	v_mfma_f32_16x16x32_bf16 v[96:99], v[212:215], v[228:231], v[96:99]
	v_mfma_f32_16x16x32_bf16 v[88:91], v[204:207], v[236:239], v[88:91]
	v_mfma_f32_16x16x32_bf16 v[80:83], v[212:215], v[236:239], v[80:83]
	v_mfma_f32_16x16x32_bf16 v[72:75], v[204:207], v[244:247], v[72:75]
	v_mfma_f32_16x16x32_bf16 v[64:67], v[212:215], v[244:247], v[64:67]
	s_barrier
	s_setprio 0
	s_add_i32 s58, s58, s26
	v_lshl_add_u64 v[168:169], s[0:1], 0, v[144:145]
	s_mov_b32 m0, s58
	ds_read_b128 v[216:219], v197 offset:16384
	ds_read_b128 v[220:223], v197 offset:17408
	ds_read_b128 v[224:227], v197 offset:18432
	ds_read_b128 v[228:231], v197 offset:19456
	ds_read_b128 v[232:235], v197 offset:20480
	ds_read_b128 v[236:239], v197 offset:21504
	ds_read_b128 v[240:243], v197 offset:22528
	ds_read_b128 v[244:247], v197 offset:23552
	global_load_lds_dwordx4 v[168:169], off
	s_add_i32 m0, s58, 0x2000
	s_add_u32 s58, s0, 0x40000
	v_lshl_add_u64 v[172:173], s[0:1], 0, v[150:151]
	s_addc_u32 s59, s1, 0
	s_add_i32 s60, s60, s26
	global_load_lds_dwordx4 v[172:173], off
	v_lshl_add_u64 v[184:185], s[58:59], 0, v[144:145]
	s_mov_b32 m0, s60
	v_lshl_add_u64 v[186:187], s[6:7], 0, v[152:153]
	global_load_lds_dwordx4 v[184:185], off
	v_lshl_add_u64 v[184:185], s[58:59], 0, v[150:151]
	s_add_i32 m0, s60, 0x2000
	s_nop 0
	global_load_lds_dwordx4 v[184:185], off
	v_lshl_add_u64 v[184:185], s[6:7], 0, v[154:155]
	s_mov_b32 m0, s27
	s_nop 0
	global_load_lds_dwordx4 v[184:185], off
	s_mov_b32 m0, s28
	s_nop 0
	global_load_lds_dwordx4 v[186:187], off
	s_waitcnt vmcnt(16)
	s_cmp_lg_u32 vcc_lo, 0
	s_cbranch_scc1 .Lgu_relaxed1
	s_waitcnt vmcnt(8)
.Lgu_relaxed1:
	s_waitcnt lgkmcnt(0)
	.p2alignl 3, 3212836864
	s_setprio 1
	s_barrier
	v_mfma_f32_16x16x32_bf16 v[60:63], v[132:135], v[216:219], v[60:63]
	v_mfma_f32_16x16x32_bf16 v[52:55], v[140:143], v[216:219], v[52:55]
	v_mfma_f32_16x16x32_bf16 v[44:47], v[132:135], v[224:227], v[44:47]
	v_mfma_f32_16x16x32_bf16 v[36:39], v[140:143], v[224:227], v[36:39]
	v_mfma_f32_16x16x32_bf16 v[28:31], v[132:135], v[232:235], v[28:31]
	v_mfma_f32_16x16x32_bf16 v[20:23], v[140:143], v[232:235], v[20:23]
	v_mfma_f32_16x16x32_bf16 v[12:15], v[132:135], v[240:243], v[12:15]
	v_mfma_f32_16x16x32_bf16 v[4:7], v[140:143], v[240:243], v[4:7]
	v_mfma_f32_16x16x32_bf16 v[60:63], v[136:139], v[220:223], v[60:63]
	v_mfma_f32_16x16x32_bf16 v[52:55], v[180:183], v[220:223], v[52:55]
	v_mfma_f32_16x16x32_bf16 v[44:47], v[136:139], v[228:231], v[44:47]
	v_mfma_f32_16x16x32_bf16 v[36:39], v[180:183], v[228:231], v[36:39]
	v_mfma_f32_16x16x32_bf16 v[28:31], v[136:139], v[236:239], v[28:31]
	v_mfma_f32_16x16x32_bf16 v[20:23], v[180:183], v[236:239], v[20:23]
	v_mfma_f32_16x16x32_bf16 v[12:15], v[136:139], v[244:247], v[12:15]
	v_mfma_f32_16x16x32_bf16 v[4:7], v[180:183], v[244:247], v[4:7]
	s_setprio 0
	s_setprio 1
	v_mfma_f32_16x16x32_bf16 v[56:59], v[200:203], v[216:219], v[56:59]
	v_mfma_f32_16x16x32_bf16 v[48:51], v[208:211], v[216:219], v[48:51]
	v_mfma_f32_16x16x32_bf16 v[40:43], v[200:203], v[224:227], v[40:43]
	v_mfma_f32_16x16x32_bf16 v[32:35], v[208:211], v[224:227], v[32:35]
	v_mfma_f32_16x16x32_bf16 v[24:27], v[200:203], v[232:235], v[24:27]
	v_mfma_f32_16x16x32_bf16 v[16:19], v[208:211], v[232:235], v[16:19]
	v_mfma_f32_16x16x32_bf16 v[8:11], v[200:203], v[240:243], v[8:11]
	v_mfma_f32_16x16x32_bf16 v[0:3], v[208:211], v[240:243], v[0:3]
	v_mfma_f32_16x16x32_bf16 v[56:59], v[204:207], v[220:223], v[56:59]
	v_mfma_f32_16x16x32_bf16 v[48:51], v[212:215], v[220:223], v[48:51]
	v_mfma_f32_16x16x32_bf16 v[40:43], v[204:207], v[228:231], v[40:43]
	v_mfma_f32_16x16x32_bf16 v[32:35], v[212:215], v[228:231], v[32:35]
	v_mfma_f32_16x16x32_bf16 v[24:27], v[204:207], v[236:239], v[24:27]
	v_mfma_f32_16x16x32_bf16 v[16:19], v[212:215], v[236:239], v[16:19]
	v_mfma_f32_16x16x32_bf16 v[8:11], v[204:207], v[244:247], v[8:11]
	v_mfma_f32_16x16x32_bf16 v[0:3], v[212:215], v[244:247], v[0:3]
	s_barrier
; #define PG8_STAGE(bufoff, gbase, voff) do { _Pragma("unroll") for (int _i = 0; _i < 2; ++_i) \
;         __builtin_amdgcn_global_load_lds((const unsigned*)((const char*)(gbase) + (voff)[_i]), (PG8_LAS unsigned*)(lds + (bufoff) + ldsw + _i * 8192), 16, 0, 0); } while (0)
; #define PG8_LDA(dst, b, h) do { _Pragma("unroll") for (int m = 0; m < 4; ++m) _Pragma("unroll") for (int k = 0; k < 2; ++k) dst[m][k] = *(const PG8_LAS bf16x8*)(lds + PG8_SA(b, h) + aoff + m * 2048 + k * 1024); } while (0)
; #define PG8_LDB(dst, b, h) do { _Pragma("unroll") for (int n = 0; n < 2; ++n) _Pragma("unroll") for (int k = 0; k < 2; ++k) dst[n][k] = *(const PG8_LAS bf16x8*)(lds + PG8_SB(b, h) + boff + n * 2048 + k * 1024); } while (0)
; #define PG8_MMA(ai, bj, At, Bt) do { __builtin_amdgcn_s_setprio(1); _Pragma("unroll") for (int m = 0; m < 4; ++m) _Pragma("unroll") for (int n = 0; n < 2; ++n) _Pragma("unroll") for (int k = 0; k < 2; ++k) \
;         acc[ai][bj][m][n] = __builtin_amdgcn_mfma_f32_16x16x32_bf16(Bt[n][k], At[m][k], acc[ai][bj][m][n], 0, 0, 0); __builtin_amdgcn_s_setprio(0); } while (0)
; #define PG8_WAIT_V(n) asm volatile("s_waitcnt vmcnt(" #n ")" ::: "memory")
; #define PG8_WAIT_L(n) asm volatile("s_waitcnt lgkmcnt(" #n ")" ::: "memory")
; #define PG8_BAR __builtin_amdgcn_s_barrier()
; #define PG8_SCHED __builtin_amdgcn_sched_barrier(0)
; template <class Epi, class Sched, bool ALIGN_EPI = false, bool SP2 = false>
; __device__ __forceinline__ void gemm_phase(PG8_LAS unsigned char* lds, const Gemm g, const Sched& S, const Epi& E) {
;     ...
;             PG8_LDB(B0, 1, 0); PG8_LDB(B1, 1, 1); PG8_SCHED; PG8_LDA(At, 1, 0); PG8_STAGE(PG8_SA(0, 1), a2 + hstep, voffA);
;             PG8_WAIT_V(8); PG8_WAIT_L(0); PG8_BAR; PG8_MMA(0, 0, At, B0); PG8_MMA(0, 1, At, B1); PG8_BAR; PG8_SCHED;
	s_setprio 0
	s_add_i32 s58, 0, 0x18000
	v_add_u32_e32 v162, s58, v165
	s_add_i32 s59, 0, 0x1c000
	ds_read_b128 v[132:135], v162
	ds_read_b128 v[136:139], v162 offset:1024
	ds_read_b128 v[140:143], v162 offset:2048
	ds_read_b128 v[180:183], v162 offset:3072
	v_add_u32_e32 v162, s59, v165
	ds_read_b128 v[200:203], v162
	ds_read_b128 v[204:207], v162 offset:1024
	ds_read_b128 v[208:211], v162 offset:2048
	ds_read_b128 v[212:215], v162 offset:3072
	s_add_u32 s6, s6, 0x40000
	s_addc_u32 s7, s7, 0
	s_mov_b32 m0, s29
	v_lshl_add_u64 v[188:189], s[6:7], 0, v[154:155]
	ds_read_b128 v[216:219], v197 offset:32768
	ds_read_b128 v[220:223], v197 offset:33792
	ds_read_b128 v[224:227], v197 offset:34816
	ds_read_b128 v[228:231], v197 offset:35840
	ds_read_b128 v[232:235], v197 offset:36864
	ds_read_b128 v[236:239], v197 offset:37888
	ds_read_b128 v[240:243], v197 offset:38912
	ds_read_b128 v[244:247], v197 offset:39936
	global_load_lds_dwordx4 v[188:189], off
	v_lshl_add_u64 v[188:189], s[6:7], 0, v[152:153]
	s_mov_b32 m0, s30
	s_nop 0
	global_load_lds_dwordx4 v[188:189], off
	s_waitcnt vmcnt(8)
	s_waitcnt lgkmcnt(0)
	.p2alignl 3, 3212836864
	s_setprio 1
	s_barrier
	v_mfma_f32_16x16x32_bf16 v[124:127], v[132:135], v[216:219], v[124:127]
	v_mfma_f32_16x16x32_bf16 v[116:119], v[140:143], v[216:219], v[116:119]
	v_mfma_f32_16x16x32_bf16 v[108:111], v[132:135], v[224:227], v[108:111]
	v_mfma_f32_16x16x32_bf16 v[100:103], v[140:143], v[224:227], v[100:103]
	v_mfma_f32_16x16x32_bf16 v[92:95], v[132:135], v[232:235], v[92:95]
	v_mfma_f32_16x16x32_bf16 v[84:87], v[140:143], v[232:235], v[84:87]
	v_mfma_f32_16x16x32_bf16 v[76:79], v[132:135], v[240:243], v[76:79]
	v_mfma_f32_16x16x32_bf16 v[68:71], v[140:143], v[240:243], v[68:71]
	v_mfma_f32_16x16x32_bf16 v[124:127], v[136:139], v[220:223], v[124:127]
	v_mfma_f32_16x16x32_bf16 v[116:119], v[180:183], v[220:223], v[116:119]
	v_mfma_f32_16x16x32_bf16 v[108:111], v[136:139], v[228:231], v[108:111]
	v_mfma_f32_16x16x32_bf16 v[100:103], v[180:183], v[228:231], v[100:103]
	v_mfma_f32_16x16x32_bf16 v[92:95], v[136:139], v[236:239], v[92:95]
	v_mfma_f32_16x16x32_bf16 v[84:87], v[180:183], v[236:239], v[84:87]
	v_mfma_f32_16x16x32_bf16 v[76:79], v[136:139], v[244:247], v[76:79]
	v_mfma_f32_16x16x32_bf16 v[68:71], v[180:183], v[244:247], v[68:71]
	s_setprio 0
	s_setprio 1
	v_mfma_f32_16x16x32_bf16 v[120:123], v[200:203], v[216:219], v[120:123]
	v_mfma_f32_16x16x32_bf16 v[112:115], v[208:211], v[216:219], v[112:115]
	v_mfma_f32_16x16x32_bf16 v[104:107], v[200:203], v[224:227], v[104:107]
	v_mfma_f32_16x16x32_bf16 v[96:99], v[208:211], v[224:227], v[96:99]
	v_mfma_f32_16x16x32_bf16 v[88:91], v[200:203], v[232:235], v[88:91]
	v_mfma_f32_16x16x32_bf16 v[80:83], v[208:211], v[232:235], v[80:83]
	v_mfma_f32_16x16x32_bf16 v[72:75], v[200:203], v[240:243], v[72:75]
	v_mfma_f32_16x16x32_bf16 v[64:67], v[208:211], v[240:243], v[64:67]
	v_mfma_f32_16x16x32_bf16 v[120:123], v[204:207], v[220:223], v[120:123]
	v_mfma_f32_16x16x32_bf16 v[112:115], v[212:215], v[220:223], v[112:115]
	v_mfma_f32_16x16x32_bf16 v[104:107], v[204:207], v[228:231], v[104:107]
	v_mfma_f32_16x16x32_bf16 v[96:99], v[212:215], v[228:231], v[96:99]
	v_mfma_f32_16x16x32_bf16 v[88:91], v[204:207], v[236:239], v[88:91]
	v_mfma_f32_16x16x32_bf16 v[80:83], v[212:215], v[236:239], v[80:83]
	v_mfma_f32_16x16x32_bf16 v[72:75], v[204:207], v[244:247], v[72:75]
	v_mfma_f32_16x16x32_bf16 v[64:67], v[212:215], v[244:247], v[64:67]
	s_barrier
; #define PG8_STAGE(bufoff, gbase, voff) do { _Pragma("unroll") for (int _i = 0; _i < 2; ++_i) \
;         __builtin_amdgcn_global_load_lds((const unsigned*)((const char*)(gbase) + (voff)[_i]), (PG8_LAS unsigned*)(lds + (bufoff) + ldsw + _i * 8192), 16, 0, 0); } while (0)
; #define PG8_LDA(dst, b, h) do { _Pragma("unroll") for (int m = 0; m < 4; ++m) _Pragma("unroll") for (int k = 0; k < 2; ++k) dst[m][k] = *(const PG8_LAS bf16x8*)(lds + PG8_SA(b, h) + aoff + m * 2048 + k * 1024); } while (0)
; #define PG8_MMA(ai, bj, At, Bt) do { __builtin_amdgcn_s_setprio(1); _Pragma("unroll") for (int m = 0; m < 4; ++m) _Pragma("unroll") for (int n = 0; n < 2; ++n) _Pragma("unroll") for (int k = 0; k < 2; ++k) \
;         acc[ai][bj][m][n] = __builtin_amdgcn_mfma_f32_16x16x32_bf16(Bt[n][k], At[m][k], acc[ai][bj][m][n], 0, 0, 0); __builtin_amdgcn_s_setprio(0); } while (0)
; #define PG8_WAIT_V(n) asm volatile("s_waitcnt vmcnt(" #n ")" ::: "memory")
; #define PG8_WAIT_L(n) asm volatile("s_waitcnt lgkmcnt(" #n ")" ::: "memory")
; #define PG8_BAR __builtin_amdgcn_s_barrier()
; #define PG8_SCHED __builtin_amdgcn_sched_barrier(0)
; template <class Epi, class Sched, bool ALIGN_EPI = false, bool SP2 = false>
; __device__ __forceinline__ void gemm_phase(PG8_LAS unsigned char* lds, const Gemm g, const Sched& S, const Epi& E) {
;     ...
;             PG8_LDA(At, 1, 1); PG8_STAGE(PG8_SB(1, 0), b3, voffB); PG8_STAGE(PG8_SB(1, 1), b3 + hstep, voffB); PG8_STAGE(PG8_SA(1, 0), a3, voffA);
;             PG8_WAIT_V(8); PG8_WAIT_L(0); PG8_BAR; PG8_MMA(1, 0, At, B0); PG8_MMA(1, 1, At, B1); PG8_BAR; PG8_SCHED;
	s_setprio 0
	s_add_i32 s6, s58, s26
	v_lshl_add_u64 v[168:169], v[168:169], 0, s[94:95]
	s_mov_b32 m0, s6
	ds_read_b128 v[216:219], v197 offset:49152
	ds_read_b128 v[220:223], v197 offset:50176
	ds_read_b128 v[224:227], v197 offset:51200
	ds_read_b128 v[228:231], v197 offset:52224
	ds_read_b128 v[232:235], v197 offset:53248
	ds_read_b128 v[236:239], v197 offset:54272
	ds_read_b128 v[240:243], v197 offset:55296
	ds_read_b128 v[244:247], v197 offset:56320
	global_load_lds_dwordx4 v[168:169], off
	s_add_i32 m0, s6, 0x2000
	s_add_u32 s0, s0, 0x40080
	v_lshl_add_u64 v[168:169], v[172:173], 0, s[94:95]
	s_addc_u32 s1, s1, 0
	s_add_i32 s6, s59, s26
	global_load_lds_dwordx4 v[168:169], off
	v_lshl_add_u64 v[168:169], s[0:1], 0, v[144:145]
	s_mov_b32 m0, s6
	s_nop 0
	global_load_lds_dwordx4 v[168:169], off
	v_lshl_add_u64 v[168:169], s[0:1], 0, v[150:151]
	s_add_i32 m0, s6, 0x2000
	s_nop 0
	global_load_lds_dwordx4 v[168:169], off
	v_lshl_add_u64 v[168:169], v[184:185], 0, s[94:95]
	s_mov_b32 m0, s31
	s_nop 0
	global_load_lds_dwordx4 v[168:169], off
	v_lshl_add_u64 v[168:169], v[186:187], 0, s[94:95]
	s_mov_b32 m0, s34
	s_nop 0
	global_load_lds_dwordx4 v[168:169], off
	s_waitcnt vmcnt(8)
	s_waitcnt lgkmcnt(0)
	.p2alignl 3, 3212836864
	s_setprio 1
	s_barrier
	v_mfma_f32_16x16x32_bf16 v[60:63], v[132:135], v[216:219], v[60:63]
	v_mfma_f32_16x16x32_bf16 v[52:55], v[140:143], v[216:219], v[52:55]
	v_mfma_f32_16x16x32_bf16 v[44:47], v[132:135], v[224:227], v[44:47]
	v_mfma_f32_16x16x32_bf16 v[36:39], v[140:143], v[224:227], v[36:39]
	v_mfma_f32_16x16x32_bf16 v[28:31], v[132:135], v[232:235], v[28:31]
	v_mfma_f32_16x16x32_bf16 v[20:23], v[140:143], v[232:235], v[20:23]
	v_mfma_f32_16x16x32_bf16 v[12:15], v[132:135], v[240:243], v[12:15]
	v_mfma_f32_16x16x32_bf16 v[4:7], v[140:143], v[240:243], v[4:7]
	v_mfma_f32_16x16x32_bf16 v[60:63], v[136:139], v[220:223], v[60:63]
	v_mfma_f32_16x16x32_bf16 v[52:55], v[180:183], v[220:223], v[52:55]
	v_mfma_f32_16x16x32_bf16 v[44:47], v[136:139], v[228:231], v[44:47]
	v_mfma_f32_16x16x32_bf16 v[36:39], v[180:183], v[228:231], v[36:39]
	v_mfma_f32_16x16x32_bf16 v[28:31], v[136:139], v[236:239], v[28:31]
	v_mfma_f32_16x16x32_bf16 v[20:23], v[180:183], v[236:239], v[20:23]
	v_mfma_f32_16x16x32_bf16 v[12:15], v[136:139], v[244:247], v[12:15]
	v_mfma_f32_16x16x32_bf16 v[4:7], v[180:183], v[244:247], v[4:7]
	s_setprio 0
	s_setprio 1
	v_mfma_f32_16x16x32_bf16 v[56:59], v[200:203], v[216:219], v[56:59]
	v_mfma_f32_16x16x32_bf16 v[48:51], v[208:211], v[216:219], v[48:51]
	v_mfma_f32_16x16x32_bf16 v[40:43], v[200:203], v[224:227], v[40:43]
	v_mfma_f32_16x16x32_bf16 v[32:35], v[208:211], v[224:227], v[32:35]
	v_mfma_f32_16x16x32_bf16 v[24:27], v[200:203], v[232:235], v[24:27]
	v_mfma_f32_16x16x32_bf16 v[16:19], v[208:211], v[232:235], v[16:19]
	v_mfma_f32_16x16x32_bf16 v[8:11], v[200:203], v[240:243], v[8:11]
	v_mfma_f32_16x16x32_bf16 v[0:3], v[208:211], v[240:243], v[0:3]
	v_mfma_f32_16x16x32_bf16 v[56:59], v[204:207], v[220:223], v[56:59]
	v_mfma_f32_16x16x32_bf16 v[48:51], v[212:215], v[220:223], v[48:51]
	v_mfma_f32_16x16x32_bf16 v[40:43], v[204:207], v[228:231], v[40:43]
	v_mfma_f32_16x16x32_bf16 v[32:35], v[212:215], v[228:231], v[32:35]
	v_mfma_f32_16x16x32_bf16 v[24:27], v[204:207], v[236:239], v[24:27]
	v_mfma_f32_16x16x32_bf16 v[16:19], v[212:215], v[236:239], v[16:19]
	v_mfma_f32_16x16x32_bf16 v[8:11], v[204:207], v[244:247], v[8:11]
	v_mfma_f32_16x16x32_bf16 v[0:3], v[212:215], v[244:247], v[0:3]
	s_barrier
	s_setprio 0
	s_add_i32 s57, s57, 2
	s_add_u32 s4, s4, 0x100
	s_addc_u32 s5, s5, 0
	s_add_u32 s55, s55, 0x100
	s_addc_u32 s56, s56, 0
	s_cmp_gt_u32 s57, 13
	s_cbranch_scc1 .LBB0_1650

; #define PG8_STAGE(bufoff, gbase, voff) do { _Pragma("unroll") for (int _i = 0; _i < 2; ++_i) \
;         __builtin_amdgcn_global_load_lds((const unsigned*)((const char*)(gbase) + (voff)[_i]), (PG8_LAS unsigned*)(lds + (bufoff) + ldsw + _i * 8192), 16, 0, 0); } while (0)
; #define PG8_LDA(dst, b, h) do { _Pragma("unroll") for (int m = 0; m < 4; ++m) _Pragma("unroll") for (int k = 0; k < 2; ++k) dst[m][k] = *(const PG8_LAS bf16x8*)(lds + PG8_SA(b, h) + aoff + m * 2048 + k * 1024); } while (0)
; #define PG8_LDB(dst, b, h) do { _Pragma("unroll") for (int n = 0; n < 2; ++n) _Pragma("unroll") for (int k = 0; k < 2; ++k) dst[n][k] = *(const PG8_LAS bf16x8*)(lds + PG8_SB(b, h) + boff + n * 2048 + k * 1024); } while (0)
; #define PG8_MMA(ai, bj, At, Bt) do { __builtin_amdgcn_s_setprio(1); _Pragma("unroll") for (int m = 0; m < 4; ++m) _Pragma("unroll") for (int n = 0; n < 2; ++n) _Pragma("unroll") for (int k = 0; k < 2; ++k) \
;         acc[ai][bj][m][n] = __builtin_amdgcn_mfma_f32_16x16x32_bf16(Bt[n][k], At[m][k], acc[ai][bj][m][n], 0, 0, 0); __builtin_amdgcn_s_setprio(0); } while (0)
; #define PG8_WAIT_V(n) asm volatile("s_waitcnt vmcnt(" #n ")" ::: "memory")
; #define PG8_BAR __builtin_amdgcn_s_barrier()
; template <class Epi, class Sched, bool ALIGN_EPI = false, bool SP2 = false>
; __device__ __forceinline__ void gemm_phase(PG8_LAS unsigned char* lds, const Gemm g, const Sched& S, const Epi& E) {
;     ...
;             const bool last = (t == nt - 2);
;             const char* a1 = cA + (size_t)(t + 1) * kstep;
;             const char* a2 = last ? nA : cA + (size_t)(t + 2) * kstep; const char* b2 = last ? nB : cB + (size_t)(t + 2) * kstep;
;             const char* a3 = a2 + kstep; const char* b3 = b2 + kstep;
;             if (last && has_next) S.a_ready(nxt);
;             if (last) E.pre(cur, wid, lane);
;             if constexpr (SP2) {
;             PG8_LDB(B0, 0, 0); PG8_LDB(B1, 0, 1); PG8_SCHED; PG8_LDA(At, 0, 0); PG8_STAGE(PG8_SA(1, 1), a1 + hstep, voffA);
;             PG8_WAIT_V(8); PG8_WAIT_L(0); PG8_BAR; PG8_MMA(0, 0, At, B0); PG8_MMA(0, 1, At, B1); PG8_BAR; PG8_SCHED;
;             PG8_LDA(At, 0, 1); PG8_STAGE(PG8_SB(0, 0), b2, voffB); PG8_STAGE(PG8_SB(0, 1), b2 + hstep, voffB); PG8_STAGE(PG8_SA(0, 0), a2, voffA);
;             PG8_WAIT_V(8); PG8_WAIT_L(0); PG8_BAR; PG8_MMA(1, 0, At, B0); PG8_MMA(1, 1, At, B1); PG8_BAR; PG8_SCHED;
.LBB0_1900:
	s_add_u32 s0, s6, 0x100
	s_addc_u32 s1, s7, 0
	s_add_i32 s60, 0, 0x10000
	s_cmp_eq_u32 s59, 40
	s_cselect_b32 s25, s41, s1
	s_cselect_b32 s24, s40, s0
	s_cselect_b32 s5, s49, s58
	s_cselect_b32 s4, s48, s57
	s_add_i32 s61, 0, 0x14000
	v_add_u32_e32 v160, s60, v143
	v_add_u32_e32 v172, s61, v143
	ds_read_b128 v[138:141], v160
	ds_read_b128 v[152:155], v160 offset:1024
	ds_read_b128 v[156:159], v160 offset:2048
	ds_read_b128 v[160:163], v160 offset:3072
	ds_read_b128 v[164:167], v172
	ds_read_b128 v[168:171], v172 offset:1024
	ds_read_b128 v[180:183], v172 offset:2048
	ds_read_b128 v[198:201], v172 offset:3072
	v_lshl_add_u64 v[172:173], s[6:7], 0, v[134:135]
	s_add_i32 m0, s30, 0xc000
	ds_read_b128 v[202:205], v151
	ds_read_b128 v[206:209], v151 offset:1024
	ds_read_b128 v[210:213], v151 offset:2048
	ds_read_b128 v[214:217], v151 offset:3072
	ds_read_b128 v[218:221], v151 offset:4096
	ds_read_b128 v[222:225], v151 offset:5120
	ds_read_b128 v[226:229], v151 offset:6144
	ds_read_b128 v[230:233], v151 offset:7168
	global_load_lds_dwordx4 v[172:173], off
	v_lshl_add_u64 v[172:173], s[6:7], 0, v[136:137]
	s_add_i32 m0, s30, 0xe000
	s_nop 0
	global_load_lds_dwordx4 v[172:173], off
	s_waitcnt vmcnt(8)
	s_waitcnt lgkmcnt(0)
	.p2alignl 3, 3212836864
	s_setprio 1
	s_barrier
	v_mfma_f32_16x16x32_bf16 v[124:127], v[138:141], v[202:205], v[124:127]
	v_mfma_f32_16x16x32_bf16 v[120:123], v[156:159], v[202:205], v[120:123]
	v_mfma_f32_16x16x32_bf16 v[108:111], v[138:141], v[210:213], v[108:111]
	v_mfma_f32_16x16x32_bf16 v[104:107], v[156:159], v[210:213], v[104:107]
	v_mfma_f32_16x16x32_bf16 v[92:95], v[138:141], v[218:221], v[92:95]
	v_mfma_f32_16x16x32_bf16 v[88:91], v[156:159], v[218:221], v[88:91]
	v_mfma_f32_16x16x32_bf16 v[76:79], v[138:141], v[226:229], v[76:79]
	v_mfma_f32_16x16x32_bf16 v[72:75], v[156:159], v[226:229], v[72:75]
	v_mfma_f32_16x16x32_bf16 v[124:127], v[152:155], v[206:209], v[124:127]
	v_mfma_f32_16x16x32_bf16 v[120:123], v[160:163], v[206:209], v[120:123]
	v_mfma_f32_16x16x32_bf16 v[108:111], v[152:155], v[214:217], v[108:111]
	v_mfma_f32_16x16x32_bf16 v[104:107], v[160:163], v[214:217], v[104:107]
	v_mfma_f32_16x16x32_bf16 v[92:95], v[152:155], v[222:225], v[92:95]
	v_mfma_f32_16x16x32_bf16 v[88:91], v[160:163], v[222:225], v[88:91]
	v_mfma_f32_16x16x32_bf16 v[76:79], v[152:155], v[230:233], v[76:79]
	v_mfma_f32_16x16x32_bf16 v[72:75], v[160:163], v[230:233], v[72:75]
	s_setprio 0
	s_setprio 1
	v_mfma_f32_16x16x32_bf16 v[116:119], v[164:167], v[202:205], v[116:119]
	v_mfma_f32_16x16x32_bf16 v[112:115], v[180:183], v[202:205], v[112:115]
	v_mfma_f32_16x16x32_bf16 v[100:103], v[164:167], v[210:213], v[100:103]
	v_mfma_f32_16x16x32_bf16 v[96:99], v[180:183], v[210:213], v[96:99]
	v_mfma_f32_16x16x32_bf16 v[84:87], v[164:167], v[218:221], v[84:87]
	v_mfma_f32_16x16x32_bf16 v[80:83], v[180:183], v[218:221], v[80:83]
	v_mfma_f32_16x16x32_bf16 v[68:71], v[164:167], v[226:229], v[68:71]
	v_mfma_f32_16x16x32_bf16 v[64:67], v[180:183], v[226:229], v[64:67]
	v_mfma_f32_16x16x32_bf16 v[116:119], v[168:171], v[206:209], v[116:119]
	v_mfma_f32_16x16x32_bf16 v[112:115], v[198:201], v[206:209], v[112:115]
	v_mfma_f32_16x16x32_bf16 v[100:103], v[168:171], v[214:217], v[100:103]
	v_mfma_f32_16x16x32_bf16 v[96:99], v[198:201], v[214:217], v[96:99]
	v_mfma_f32_16x16x32_bf16 v[84:87], v[168:171], v[222:225], v[84:87]
	v_mfma_f32_16x16x32_bf16 v[80:83], v[198:201], v[222:225], v[80:83]
	v_mfma_f32_16x16x32_bf16 v[68:71], v[168:171], v[230:233], v[68:71]
	v_mfma_f32_16x16x32_bf16 v[64:67], v[198:201], v[230:233], v[64:67]
	s_barrier
	s_setprio 0
	s_add_i32 s6, s60, s29
	v_lshl_add_u64 v[172:173], s[4:5], 0, v[144:145]
	s_mov_b32 m0, s6
	ds_read_b128 v[202:205], v151 offset:16384
	ds_read_b128 v[206:209], v151 offset:17408
	ds_read_b128 v[210:213], v151 offset:18432
	ds_read_b128 v[214:217], v151 offset:19456
	ds_read_b128 v[218:221], v151 offset:20480
	ds_read_b128 v[222:225], v151 offset:21504
	ds_read_b128 v[226:229], v151 offset:22528
	ds_read_b128 v[230:233], v151 offset:23552
	global_load_lds_dwordx4 v[172:173], off
	s_add_i32 m0, s6, 0x2000
	s_add_u32 s6, s4, 0xb0000
	v_lshl_add_u64 v[184:185], s[4:5], 0, v[128:129]
	s_addc_u32 s7, s5, 0
	s_add_i32 s60, s61, s29
	global_load_lds_dwordx4 v[184:185], off
	v_lshl_add_u64 v[186:187], s[6:7], 0, v[144:145]
	s_mov_b32 m0, s60
	v_lshl_add_u64 v[188:189], s[24:25], 0, v[130:131]
	global_load_lds_dwordx4 v[186:187], off
	v_lshl_add_u64 v[186:187], s[6:7], 0, v[128:129]
	s_add_i32 m0, s60, 0x2000
	s_nop 0
	global_load_lds_dwordx4 v[186:187], off
	v_lshl_add_u64 v[186:187], s[24:25], 0, v[132:133]
	s_mov_b32 m0, s30
	s_nop 0
	global_load_lds_dwordx4 v[186:187], off
	s_mov_b32 m0, s31
	s_nop 0
	global_load_lds_dwordx4 v[188:189], off
	s_waitcnt vmcnt(8)
	s_waitcnt lgkmcnt(0)
	.p2alignl 3, 3212836864
	s_setprio 1
	s_barrier
; #define PG8_STAGE(bufoff, gbase, voff) do { _Pragma("unroll") for (int _i = 0; _i < 2; ++_i) \
;         __builtin_amdgcn_global_load_lds((const unsigned*)((const char*)(gbase) + (voff)[_i]), (PG8_LAS unsigned*)(lds + (bufoff) + ldsw + _i * 8192), 16, 0, 0); } while (0)
; #define PG8_LDA(dst, b, h) do { _Pragma("unroll") for (int m = 0; m < 4; ++m) _Pragma("unroll") for (int k = 0; k < 2; ++k) dst[m][k] = *(const PG8_LAS bf16x8*)(lds + PG8_SA(b, h) + aoff + m * 2048 + k * 1024); } while (0)
; #define PG8_LDB(dst, b, h) do { _Pragma("unroll") for (int n = 0; n < 2; ++n) _Pragma("unroll") for (int k = 0; k < 2; ++k) dst[n][k] = *(const PG8_LAS bf16x8*)(lds + PG8_SB(b, h) + boff + n * 2048 + k * 1024); } while (0)
; #define PG8_MMA(ai, bj, At, Bt) do { __builtin_amdgcn_s_setprio(1); _Pragma("unroll") for (int m = 0; m < 4; ++m) _Pragma("unroll") for (int n = 0; n < 2; ++n) _Pragma("unroll") for (int k = 0; k < 2; ++k) \
;         acc[ai][bj][m][n] = __builtin_amdgcn_mfma_f32_16x16x32_bf16(Bt[n][k], At[m][k], acc[ai][bj][m][n], 0, 0, 0); __builtin_amdgcn_s_setprio(0); } while (0)
; #define PG8_WAIT_V(n) asm volatile("s_waitcnt vmcnt(" #n ")" ::: "memory")
; #define PG8_WAIT_L(n) asm volatile("s_waitcnt lgkmcnt(" #n ")" ::: "memory")
; #define PG8_BAR __builtin_amdgcn_s_barrier()
; #define PG8_SCHED __builtin_amdgcn_sched_barrier(0)
; template <class Epi, class Sched, bool ALIGN_EPI = false, bool SP2 = false>
; __device__ __forceinline__ void gemm_phase(PG8_LAS unsigned char* lds, const Gemm g, const Sched& S, const Epi& E) {
;     ...
;             PG8_WAIT_V(8); PG8_WAIT_L(0); PG8_BAR; PG8_MMA(1, 0, At, B0); PG8_MMA(1, 1, At, B1); PG8_BAR; PG8_SCHED;
;             PG8_LDB(B0, 1, 0); PG8_LDB(B1, 1, 1); PG8_SCHED; PG8_LDA(At, 1, 0); PG8_STAGE(PG8_SA(0, 1), a2 + hstep, voffA);
;             PG8_WAIT_V(8); PG8_WAIT_L(0); PG8_BAR; PG8_MMA(0, 0, At, B0); PG8_MMA(0, 1, At, B1); PG8_BAR; PG8_SCHED;
	v_mfma_f32_16x16x32_bf16 v[60:63], v[138:141], v[202:205], v[60:63]
	v_mfma_f32_16x16x32_bf16 v[56:59], v[156:159], v[202:205], v[56:59]
	v_mfma_f32_16x16x32_bf16 v[44:47], v[138:141], v[210:213], v[44:47]
	v_mfma_f32_16x16x32_bf16 v[40:43], v[156:159], v[210:213], v[40:43]
	v_mfma_f32_16x16x32_bf16 v[28:31], v[138:141], v[218:221], v[28:31]
	v_mfma_f32_16x16x32_bf16 v[24:27], v[156:159], v[218:221], v[24:27]
	v_mfma_f32_16x16x32_bf16 v[12:15], v[138:141], v[226:229], v[12:15]
	v_mfma_f32_16x16x32_bf16 v[8:11], v[156:159], v[226:229], v[8:11]
	v_mfma_f32_16x16x32_bf16 v[60:63], v[152:155], v[206:209], v[60:63]
	v_mfma_f32_16x16x32_bf16 v[56:59], v[160:163], v[206:209], v[56:59]
	v_mfma_f32_16x16x32_bf16 v[44:47], v[152:155], v[214:217], v[44:47]
	v_mfma_f32_16x16x32_bf16 v[40:43], v[160:163], v[214:217], v[40:43]
	v_mfma_f32_16x16x32_bf16 v[28:31], v[152:155], v[222:225], v[28:31]
	v_mfma_f32_16x16x32_bf16 v[24:27], v[160:163], v[222:225], v[24:27]
	v_mfma_f32_16x16x32_bf16 v[12:15], v[152:155], v[230:233], v[12:15]
	v_mfma_f32_16x16x32_bf16 v[8:11], v[160:163], v[230:233], v[8:11]
	s_setprio 0
	s_setprio 1
	v_mfma_f32_16x16x32_bf16 v[52:55], v[164:167], v[202:205], v[52:55]
	v_mfma_f32_16x16x32_bf16 v[48:51], v[180:183], v[202:205], v[48:51]
	v_mfma_f32_16x16x32_bf16 v[36:39], v[164:167], v[210:213], v[36:39]
	v_mfma_f32_16x16x32_bf16 v[32:35], v[180:183], v[210:213], v[32:35]
	v_mfma_f32_16x16x32_bf16 v[20:23], v[164:167], v[218:221], v[20:23]
	v_mfma_f32_16x16x32_bf16 v[16:19], v[180:183], v[218:221], v[16:19]
	v_mfma_f32_16x16x32_bf16 v[4:7], v[164:167], v[226:229], v[4:7]
	v_mfma_f32_16x16x32_bf16 v[0:3], v[180:183], v[226:229], v[0:3]
	v_mfma_f32_16x16x32_bf16 v[52:55], v[168:171], v[206:209], v[52:55]
	v_mfma_f32_16x16x32_bf16 v[48:51], v[198:201], v[206:209], v[48:51]
	v_mfma_f32_16x16x32_bf16 v[36:39], v[168:171], v[214:217], v[36:39]
	v_mfma_f32_16x16x32_bf16 v[32:35], v[198:201], v[214:217], v[32:35]
	v_mfma_f32_16x16x32_bf16 v[20:23], v[168:171], v[222:225], v[20:23]
	v_mfma_f32_16x16x32_bf16 v[16:19], v[198:201], v[222:225], v[16:19]
	v_mfma_f32_16x16x32_bf16 v[4:7], v[168:171], v[230:233], v[4:7]
	v_mfma_f32_16x16x32_bf16 v[0:3], v[198:201], v[230:233], v[0:3]
	s_barrier
	s_setprio 0
	s_add_i32 s60, 0, 0x18000
	s_add_i32 s61, 0, 0x1c000
	v_add_u32_e32 v160, s60, v143
	v_add_u32_e32 v190, s61, v143
	ds_read_b128 v[138:141], v160
	ds_read_b128 v[152:155], v160 offset:1024
	ds_read_b128 v[156:159], v160 offset:2048
	ds_read_b128 v[160:163], v160 offset:3072
	ds_read_b128 v[164:167], v190
	ds_read_b128 v[168:171], v190 offset:1024
	ds_read_b128 v[180:183], v190 offset:2048
	ds_read_b128 v[198:201], v190 offset:3072
	s_add_u32 s6, s24, 0xb0000
	s_addc_u32 s7, s25, 0
	s_mov_b32 m0, s34
	v_lshl_add_u64 v[190:191], s[6:7], 0, v[132:133]
	ds_read_b128 v[202:205], v151 offset:32768
	ds_read_b128 v[206:209], v151 offset:33792
	ds_read_b128 v[210:213], v151 offset:34816
	ds_read_b128 v[214:217], v151 offset:35840
	ds_read_b128 v[218:221], v151 offset:36864
	ds_read_b128 v[222:225], v151 offset:37888
	ds_read_b128 v[226:229], v151 offset:38912
	ds_read_b128 v[230:233], v151 offset:39936
	global_load_lds_dwordx4 v[190:191], off
	v_lshl_add_u64 v[190:191], s[6:7], 0, v[130:131]
	s_mov_b32 m0, s35
	s_nop 0
	global_load_lds_dwordx4 v[190:191], off
	s_waitcnt vmcnt(8)
	s_waitcnt lgkmcnt(0)
	.p2alignl 3, 3212836864
	s_setprio 1
	s_barrier
	v_mfma_f32_16x16x32_bf16 v[124:127], v[138:141], v[202:205], v[124:127]
	v_mfma_f32_16x16x32_bf16 v[120:123], v[156:159], v[202:205], v[120:123]
	v_mfma_f32_16x16x32_bf16 v[108:111], v[138:141], v[210:213], v[108:111]
	v_mfma_f32_16x16x32_bf16 v[104:107], v[156:159], v[210:213], v[104:107]
	v_mfma_f32_16x16x32_bf16 v[92:95], v[138:141], v[218:221], v[92:95]
	v_mfma_f32_16x16x32_bf16 v[88:91], v[156:159], v[218:221], v[88:91]
	v_mfma_f32_16x16x32_bf16 v[76:79], v[138:141], v[226:229], v[76:79]
	v_mfma_f32_16x16x32_bf16 v[72:75], v[156:159], v[226:229], v[72:75]
	v_mfma_f32_16x16x32_bf16 v[124:127], v[152:155], v[206:209], v[124:127]
	v_mfma_f32_16x16x32_bf16 v[120:123], v[160:163], v[206:209], v[120:123]
	v_mfma_f32_16x16x32_bf16 v[108:111], v[152:155], v[214:217], v[108:111]
	v_mfma_f32_16x16x32_bf16 v[104:107], v[160:163], v[214:217], v[104:107]
	v_mfma_f32_16x16x32_bf16 v[92:95], v[152:155], v[222:225], v[92:95]
	v_mfma_f32_16x16x32_bf16 v[88:91], v[160:163], v[222:225], v[88:91]
	v_mfma_f32_16x16x32_bf16 v[76:79], v[152:155], v[230:233], v[76:79]
	v_mfma_f32_16x16x32_bf16 v[72:75], v[160:163], v[230:233], v[72:75]
	s_setprio 0
	s_setprio 1
	v_mfma_f32_16x16x32_bf16 v[116:119], v[164:167], v[202:205], v[116:119]
	v_mfma_f32_16x16x32_bf16 v[112:115], v[180:183], v[202:205], v[112:115]
	v_mfma_f32_16x16x32_bf16 v[100:103], v[164:167], v[210:213], v[100:103]
	v_mfma_f32_16x16x32_bf16 v[96:99], v[180:183], v[210:213], v[96:99]
	v_mfma_f32_16x16x32_bf16 v[84:87], v[164:167], v[218:221], v[84:87]
	v_mfma_f32_16x16x32_bf16 v[80:83], v[180:183], v[218:221], v[80:83]
	v_mfma_f32_16x16x32_bf16 v[68:71], v[164:167], v[226:229], v[68:71]
	v_mfma_f32_16x16x32_bf16 v[64:67], v[180:183], v[226:229], v[64:67]
	v_mfma_f32_16x16x32_bf16 v[116:119], v[168:171], v[206:209], v[116:119]
	v_mfma_f32_16x16x32_bf16 v[112:115], v[198:201], v[206:209], v[112:115]
	v_mfma_f32_16x16x32_bf16 v[100:103], v[168:171], v[214:217], v[100:103]
	v_mfma_f32_16x16x32_bf16 v[96:99], v[198:201], v[214:217], v[96:99]
	v_mfma_f32_16x16x32_bf16 v[84:87], v[168:171], v[222:225], v[84:87]
	v_mfma_f32_16x16x32_bf16 v[80:83], v[198:201], v[222:225], v[80:83]
	v_mfma_f32_16x16x32_bf16 v[68:71], v[168:171], v[230:233], v[68:71]
	v_mfma_f32_16x16x32_bf16 v[64:67], v[198:201], v[230:233], v[64:67]
	s_barrier
; #define PG8_STAGE(bufoff, gbase, voff) do { _Pragma("unroll") for (int _i = 0; _i < 2; ++_i) \
;         __builtin_amdgcn_global_load_lds((const unsigned*)((const char*)(gbase) + (voff)[_i]), (PG8_LAS unsigned*)(lds + (bufoff) + ldsw + _i * 8192), 16, 0, 0); } while (0)
; #define PG8_LDA(dst, b, h) do { _Pragma("unroll") for (int m = 0; m < 4; ++m) _Pragma("unroll") for (int k = 0; k < 2; ++k) dst[m][k] = *(const PG8_LAS bf16x8*)(lds + PG8_SA(b, h) + aoff + m * 2048 + k * 1024); } while (0)
; #define PG8_MMA(ai, bj, At, Bt) do { __builtin_amdgcn_s_setprio(1); _Pragma("unroll") for (int m = 0; m < 4; ++m) _Pragma("unroll") for (int n = 0; n < 2; ++n) _Pragma("unroll") for (int k = 0; k < 2; ++k) \
;         acc[ai][bj][m][n] = __builtin_amdgcn_mfma_f32_16x16x32_bf16(Bt[n][k], At[m][k], acc[ai][bj][m][n], 0, 0, 0); __builtin_amdgcn_s_setprio(0); } while (0)
; #define PG8_WAIT_V(n) asm volatile("s_waitcnt vmcnt(" #n ")" ::: "memory")
; #define PG8_WAIT_L(n) asm volatile("s_waitcnt lgkmcnt(" #n ")" ::: "memory")
; #define PG8_BAR __builtin_amdgcn_s_barrier()
; #define PG8_SCHED __builtin_amdgcn_sched_barrier(0)
; template <class Epi, class Sched, bool ALIGN_EPI = false, bool SP2 = false>
; __device__ __forceinline__ void gemm_phase(PG8_LAS unsigned char* lds, const Gemm g, const Sched& S, const Epi& E) {
;     ...
;             PG8_LDA(At, 1, 1); PG8_STAGE(PG8_SB(1, 0), b3, voffB); PG8_STAGE(PG8_SB(1, 1), b3 + hstep, voffB); PG8_STAGE(PG8_SA(1, 0), a3, voffA);
;             PG8_WAIT_V(8); PG8_WAIT_L(0); PG8_BAR; PG8_MMA(1, 0, At, B0); PG8_MMA(1, 1, At, B1); PG8_BAR; PG8_SCHED;
;     ...
;         if constexpr (ALIGN_EPI) { if (wr == 0) PG8_BAR; }
	s_setprio 0
	s_add_i32 s6, s60, s29
	v_lshl_add_u64 v[172:173], v[172:173], 0, s[94:95]
	s_mov_b32 m0, s6
	ds_read_b128 v[202:205], v151 offset:49152
	ds_read_b128 v[206:209], v151 offset:50176
	ds_read_b128 v[210:213], v151 offset:51200
	ds_read_b128 v[214:217], v151 offset:52224
	ds_read_b128 v[218:221], v151 offset:53248
	ds_read_b128 v[222:225], v151 offset:54272
	ds_read_b128 v[226:229], v151 offset:55296
	ds_read_b128 v[230:233], v151 offset:56320
	global_load_lds_dwordx4 v[172:173], off
	s_add_i32 m0, s6, 0x2000
	s_add_u32 s4, s4, 0xb0080
	v_lshl_add_u64 v[172:173], v[184:185], 0, s[94:95]
	s_addc_u32 s5, s5, 0
	s_add_i32 s6, s61, s29
	global_load_lds_dwordx4 v[172:173], off
	v_lshl_add_u64 v[172:173], s[4:5], 0, v[144:145]
	s_mov_b32 m0, s6
	s_nop 0
	global_load_lds_dwordx4 v[172:173], off
	v_lshl_add_u64 v[172:173], s[4:5], 0, v[128:129]
	s_add_i32 m0, s6, 0x2000
	s_nop 0
	global_load_lds_dwordx4 v[172:173], off
	v_lshl_add_u64 v[172:173], v[186:187], 0, s[94:95]
	s_mov_b32 m0, s50
	s_nop 0
	global_load_lds_dwordx4 v[172:173], off
	v_lshl_add_u64 v[172:173], v[188:189], 0, s[94:95]
	s_mov_b32 m0, s51
	s_nop 0
	global_load_lds_dwordx4 v[172:173], off
	s_waitcnt vmcnt(8)
	s_waitcnt lgkmcnt(0)
	.p2alignl 3, 3212836864
	s_setprio 1
	s_barrier
	v_mfma_f32_16x16x32_bf16 v[60:63], v[138:141], v[202:205], v[60:63]
	v_mfma_f32_16x16x32_bf16 v[56:59], v[156:159], v[202:205], v[56:59]
	v_mfma_f32_16x16x32_bf16 v[44:47], v[138:141], v[210:213], v[44:47]
	v_mfma_f32_16x16x32_bf16 v[40:43], v[156:159], v[210:213], v[40:43]
	v_mfma_f32_16x16x32_bf16 v[28:31], v[138:141], v[218:221], v[28:31]
	v_mfma_f32_16x16x32_bf16 v[24:27], v[156:159], v[218:221], v[24:27]
	v_mfma_f32_16x16x32_bf16 v[12:15], v[138:141], v[226:229], v[12:15]
	v_mfma_f32_16x16x32_bf16 v[8:11], v[156:159], v[226:229], v[8:11]
	v_mfma_f32_16x16x32_bf16 v[60:63], v[152:155], v[206:209], v[60:63]
	v_mfma_f32_16x16x32_bf16 v[56:59], v[160:163], v[206:209], v[56:59]
	v_mfma_f32_16x16x32_bf16 v[44:47], v[152:155], v[214:217], v[44:47]
	v_mfma_f32_16x16x32_bf16 v[40:43], v[160:163], v[214:217], v[40:43]
	v_mfma_f32_16x16x32_bf16 v[28:31], v[152:155], v[222:225], v[28:31]
	v_mfma_f32_16x16x32_bf16 v[24:27], v[160:163], v[222:225], v[24:27]
	v_mfma_f32_16x16x32_bf16 v[12:15], v[152:155], v[230:233], v[12:15]
	v_mfma_f32_16x16x32_bf16 v[8:11], v[160:163], v[230:233], v[8:11]
	s_setprio 0
	s_setprio 1
	v_mfma_f32_16x16x32_bf16 v[52:55], v[164:167], v[202:205], v[52:55]
	v_mfma_f32_16x16x32_bf16 v[48:51], v[180:183], v[202:205], v[48:51]
	v_mfma_f32_16x16x32_bf16 v[36:39], v[164:167], v[210:213], v[36:39]
	v_mfma_f32_16x16x32_bf16 v[32:35], v[180:183], v[210:213], v[32:35]
	v_mfma_f32_16x16x32_bf16 v[20:23], v[164:167], v[218:221], v[20:23]
	v_mfma_f32_16x16x32_bf16 v[16:19], v[180:183], v[218:221], v[16:19]
	v_mfma_f32_16x16x32_bf16 v[4:7], v[164:167], v[226:229], v[4:7]
	v_mfma_f32_16x16x32_bf16 v[0:3], v[180:183], v[226:229], v[0:3]
	v_mfma_f32_16x16x32_bf16 v[52:55], v[168:171], v[206:209], v[52:55]
	v_mfma_f32_16x16x32_bf16 v[48:51], v[198:201], v[206:209], v[48:51]
	v_mfma_f32_16x16x32_bf16 v[36:39], v[168:171], v[214:217], v[36:39]
	v_mfma_f32_16x16x32_bf16 v[32:35], v[198:201], v[214:217], v[32:35]
	v_mfma_f32_16x16x32_bf16 v[20:23], v[168:171], v[222:225], v[20:23]
	v_mfma_f32_16x16x32_bf16 v[16:19], v[198:201], v[222:225], v[16:19]
	v_mfma_f32_16x16x32_bf16 v[4:7], v[168:171], v[230:233], v[4:7]
	v_mfma_f32_16x16x32_bf16 v[0:3], v[198:201], v[230:233], v[0:3]
	s_barrier
	s_setprio 0
	s_add_i32 s59, s59, 2
	s_add_u32 s57, s57, 0x100
	s_addc_u32 s58, s58, 0
	s_cmp_gt_u32 s59, 41
	s_mov_b64 s[6:7], s[0:1]
	s_cbranch_scc0 .LBB0_1900
	s_and_b64 vcc, exec, s[46:47]
	s_cbranch_vccz .LBB0_1903
	s_barrier
